# P1 and P7 token loops rewritten: all loads of 4 tokens issued together (no per-piece vmcnt(0) on the pos-embed path), interleaved wave reductions; P4 conv packed
# speedup vs baseline: 1.0587x; 1.0156x over previous
.LBB0_155:
	v_lshl_add_u64 v[2:3], s[2:3], 0, v[60:61]
	s_waitcnt vmcnt(23)
	v_add_co_u32_e32 v10, vcc, 0x4000, v2
	v_lshl_add_u64 v[8:9], s[6:7], 0, v[60:61]
	s_waitcnt vmcnt(22)
	v_addc_co_u32_e32 v11, vcc, 0, v3, vcc
	global_load_dword v15, v[8:9], off
	v_add_co_u32_e32 v8, vcc, 0xd000, v2
	v_lshl_add_u64 v[6:7], s[16:17], 0, v[60:61]
	s_nop 0
	v_addc_co_u32_e32 v9, vcc, 0, v3, vcc
	s_waitcnt vmcnt(22)
	v_add_co_u32_e32 v12, vcc, 0x16000, v2
	global_load_dword v14, v[6:7], off
	s_waitcnt vmcnt(22)
	v_addc_co_u32_e32 v13, vcc, 0, v3, vcc
	global_load_dword v16, v[10:11], off
	global_load_dword v17, v[8:9], off
	v_add_co_u32_e32 v8, vcc, 0x1f000, v2
	s_add_u32 s2, s2, 0x800
	s_nop 0
	v_addc_co_u32_e32 v9, vcc, 0, v3, vcc
	v_add_co_u32_e32 v10, vcc, 0x28000, v2
	global_load_dword v18, v[12:13], off
	global_load_dword v19, v[8:9], off
	v_addc_co_u32_e32 v11, vcc, 0, v3, vcc
	v_add_co_u32_e32 v8, vcc, 0x31000, v2
	s_addc_u32 s3, s3, 0
	s_nop 0
	v_addc_co_u32_e32 v9, vcc, 0, v3, vcc
	v_add_co_u32_e32 v12, vcc, 0x3a000, v2
	global_load_dword v20, v[10:11], off
	global_load_dword v21, v[8:9], off
	v_addc_co_u32_e32 v13, vcc, 0, v3, vcc
	v_add_co_u32_e32 v8, vcc, 0x43000, v2
	s_add_u32 s16, s16, 0x800
	s_nop 0
	v_addc_co_u32_e32 v9, vcc, 0, v3, vcc
	v_add_co_u32_e32 v10, vcc, 0x4c000, v2
	global_load_dword v22, v[12:13], off
	global_load_dword v23, v[8:9], off
	v_addc_co_u32_e32 v11, vcc, 0, v3, vcc
	v_add_co_u32_e32 v8, vcc, 0x55000, v2
	global_load_dword v24, v[10:11], off
	s_nop 0
	v_addc_co_u32_e32 v9, vcc, 0, v3, vcc
	v_add_co_u32_e32 v10, vcc, 0x5e000, v2
	s_addc_u32 s17, s17, 0
	s_nop 0
	v_addc_co_u32_e32 v11, vcc, 0, v3, vcc
	v_add_co_u32_e32 v12, vcc, 0x67000, v2
	global_load_dword v25, v[8:9], off
	global_load_dword v26, v[10:11], off
	v_addc_co_u32_e32 v13, vcc, 0, v3, vcc
	v_add_co_u32_e32 v8, vcc, 0x70000, v2
	s_add_u32 s6, s6, 0x800
	s_nop 0
	v_addc_co_u32_e32 v9, vcc, 0, v3, vcc
	v_add_co_u32_e32 v10, vcc, 0x79000, v2
	global_load_dword v27, v[12:13], off
	global_load_dword v28, v[8:9], off
	v_addc_co_u32_e32 v11, vcc, 0, v3, vcc
	v_add_co_u32_e32 v8, vcc, 0x82000, v2
	s_addc_u32 s7, s7, 0
	s_nop 0
	v_addc_co_u32_e32 v9, vcc, 0, v3, vcc
	v_add_co_u32_e32 v12, vcc, 0x8b000, v2
	global_load_dword v29, v[10:11], off
	global_load_dword v30, v[8:9], off
	v_addc_co_u32_e32 v13, vcc, 0, v3, vcc
	v_add_co_u32_e32 v6, vcc, 0x1000, v6
	s_nop 1
	v_addc_co_u32_e32 v7, vcc, 0, v7, vcc
	v_add_co_u32_e32 v8, vcc, 0x5000, v2
	global_load_dword v31, v[6:7], off
	s_nop 0
	v_addc_co_u32_e32 v9, vcc, 0, v3, vcc
	v_add_co_u32_e32 v6, vcc, 0xe000, v2
	s_nop 1
	v_addc_co_u32_e32 v7, vcc, 0, v3, vcc
	v_add_co_u32_e32 v10, vcc, 0x17000, v2
	global_load_dword v32, v[8:9], off
	global_load_dword v33, v[6:7], off
	v_addc_co_u32_e32 v11, vcc, 0, v3, vcc
	v_add_co_u32_e32 v6, vcc, 0x20000, v2
	s_nop 1
	v_addc_co_u32_e32 v7, vcc, 0, v3, vcc
	v_add_co_u32_e32 v8, vcc, 0x29000, v2
	global_load_dword v34, v[10:11], off
	global_load_dword v35, v[6:7], off
	v_addc_co_u32_e32 v9, vcc, 0, v3, vcc
	v_add_co_u32_e32 v6, vcc, 0x32000, v2
	s_nop 1
	v_addc_co_u32_e32 v7, vcc, 0, v3, vcc
	v_add_co_u32_e32 v10, vcc, 0x3b000, v2
	global_load_dword v36, v[8:9], off
	global_load_dword v37, v[6:7], off
	v_addc_co_u32_e32 v11, vcc, 0, v3, vcc
	v_add_co_u32_e32 v6, vcc, 0x44000, v2
	s_nop 1
	v_addc_co_u32_e32 v7, vcc, 0, v3, vcc
	v_add_co_u32_e32 v8, vcc, 0x4d000, v2
	global_load_dword v38, v[10:11], off
	global_load_dword v39, v[6:7], off
	v_addc_co_u32_e32 v9, vcc, 0, v3, vcc
	v_add_co_u32_e32 v6, vcc, 0x56000, v2
	s_nop 1
	v_addc_co_u32_e32 v7, vcc, 0, v3, vcc
	v_add_co_u32_e32 v10, vcc, 0x5f000, v2
	global_load_dword v40, v[8:9], off
	global_load_dword v41, v[6:7], off
	v_addc_co_u32_e32 v11, vcc, 0, v3, vcc
	v_add_co_u32_e32 v6, vcc, 0x68000, v2
	s_nop 1
	v_addc_co_u32_e32 v7, vcc, 0, v3, vcc
	v_add_co_u32_e32 v8, vcc, 0x71000, v2
	global_load_dword v42, v[10:11], off
	global_load_dword v43, v[6:7], off
	v_addc_co_u32_e32 v9, vcc, 0, v3, vcc
	v_add_co_u32_e32 v6, vcc, 0x7a000, v2
	s_nop 1
	v_addc_co_u32_e32 v7, vcc, 0, v3, vcc
	v_add_co_u32_e32 v10, vcc, 0x83000, v2
	global_load_dword v44, v[8:9], off
	global_load_dword v45, v[6:7], off
	v_addc_co_u32_e32 v11, vcc, 0, v3, vcc
	v_add_co_u32_e32 v2, vcc, 0x8c000, v2
	s_nop 1
	v_addc_co_u32_e32 v3, vcc, 0, v3, vcc
	global_load_dword v6, v[10:11], off
	global_load_dword v7, v[2:3], off
	global_load_dword v8, v[12:13], off
	s_waitcnt vmcnt(32)
	v_add_f32_e32 v2, v14, v16
	s_waitcnt vmcnt(31)
	v_add_f32_e32 v2, v2, v17
	s_waitcnt vmcnt(30)
	v_add_f32_e32 v2, v2, v18
	s_waitcnt vmcnt(29)
	v_add_f32_e32 v2, v2, v19
	s_waitcnt vmcnt(28)
	v_add_f32_e32 v2, v2, v20
	s_waitcnt vmcnt(27)
	v_add_f32_e32 v2, v2, v21
	s_waitcnt vmcnt(26)
	v_add_f32_e32 v2, v2, v22
	s_waitcnt vmcnt(25)
	v_add_f32_e32 v2, v2, v23
	s_waitcnt vmcnt(24)
	v_add_f32_e32 v2, v2, v24
	s_waitcnt vmcnt(23)
	v_add_f32_e32 v2, v2, v25
	s_waitcnt vmcnt(16)
	v_add_f32_e32 v3, v31, v32
	s_waitcnt vmcnt(15)
	v_add_f32_e32 v3, v3, v33
	v_add_f32_e32 v2, v2, v26
	v_add_f32_e32 v2, v2, v27
	v_add_f32_e32 v2, v2, v28
	v_add_co_u32_e32 v4, vcc, 0x200, v4
	v_add_f32_e32 v2, v2, v29
	s_xor_b64 s[26:27], vcc, -1
	v_add_f32_e32 v2, v2, v30
	s_waitcnt vmcnt(14)
	v_add_f32_e32 v3, v3, v34
	s_waitcnt vmcnt(13)
	v_add_f32_e32 v3, v3, v35
	s_and_b64 s[26:27], exec, s[26:27]
	s_or_b64 s[4:5], s[26:27], s[4:5]
	s_waitcnt vmcnt(12)
	v_add_f32_e32 v3, v3, v36
	s_waitcnt vmcnt(11)
	v_add_f32_e32 v3, v3, v37
	s_waitcnt vmcnt(10)
	v_add_f32_e32 v3, v3, v38
	s_waitcnt vmcnt(9)
	v_add_f32_e32 v3, v3, v39
	s_waitcnt vmcnt(8)
	v_add_f32_e32 v3, v3, v40
	s_waitcnt vmcnt(7)
	v_add_f32_e32 v3, v3, v41
	s_waitcnt vmcnt(6)
	v_add_f32_e32 v3, v3, v42
	s_waitcnt vmcnt(5)
	v_add_f32_e32 v3, v3, v43
	s_waitcnt vmcnt(4)
	v_add_f32_e32 v3, v3, v44
	s_waitcnt vmcnt(3)
	v_add_f32_e32 v3, v3, v45
	s_waitcnt vmcnt(2)
	v_add_f32_e32 v3, v3, v6
	s_waitcnt vmcnt(1)
	v_add_f32_e32 v3, v3, v7
	v_add_f32_e32 v3, 1.0, v3
	s_waitcnt vmcnt(0)
	v_add_f32_e32 v2, v2, v8
	v_mul_f32_e32 v3, v15, v3
	ds_write2st64_b32 v5, v3, v2 offset1:16
	v_add_u32_e32 v5, 0x800, v5
	s_andn2_b64 exec, exec, s[4:5]
	s_cbranch_execnz .LBB0_155
	s_or_b64 exec, exec, s[4:5]
	s_waitcnt lgkmcnt(0)
	s_barrier
	ds_read_b128 v[2:5], v71
	ds_read_b128 v[6:9], v71 offset:1024
	ds_read_b128 v[10:13], v71 offset:4096
	ds_read_b128 v[14:17], v71 offset:5120
	ds_read_b128 v[18:21], v71 offset:2048
	ds_read_b128 v[22:25], v71 offset:3072
	ds_read_b128 v[26:29], v71 offset:6144
	ds_read_b128 v[30:33], v71 offset:7168
	v_lshlrev_b32_e32 v52, 2, v50
	v_lshlrev_b32_e32 v78, 3, v1
	s_cmpk_lt_u32 s25, 0x80
	s_cselect_b32 s26, 0, 1
	s_cmp_eq_u32 s26, 0
	s_cbranch_scc1 .Lp1n_norow
	s_lshl_b32 s0, s19, 4
	s_and_b32 s0, s0, 0xfc00
	s_add_u32 s2, s74, 0x94000
	s_addc_u32 s3, s75, 0
	s_add_u32 s2, s2, s0
	s_addc_u32 s3, s3, 0
	global_load_dwordx4 v[180:183], v52, s[2:3]
	s_add_u32 s2, s2, 0x10000
	s_addc_u32 s3, s3, 0
	global_load_dwordx4 v[184:187], v52, s[2:3]
.Lp1n_norow:
	s_waitcnt lgkmcnt(0)
	s_add_u32 s0, s19, 0
	s_cmpk_lt_u32 s0, 0x2000
	s_cselect_b32 s2, s8, s10
	s_cselect_b32 s3, s9, s11
	s_and_b32 s1, s0, 0x1fff
	s_lshl_b32 s4, s1, 12
	s_add_u32 s2, s2, s4
	s_addc_u32 s3, s3, 0
	global_load_dwordx4 v[84:87], v52, s[2:3] offset:0 nt
	global_load_dwordx4 v[88:91], v52, s[2:3] offset:1024 nt
	global_load_dwordx4 v[92:95], v52, s[2:3] offset:2048 nt
	global_load_dwordx4 v[96:99], v52, s[2:3] offset:3072 nt
	s_cmp_eq_u32 s26, 0
	s_cbranch_scc1 .Lp1n_nocol_0
	s_and_b32 s4, s0, 63
	s_lshl_b32 s4, s4, 10
	s_add_u32 s2, s74, 0x94000
	s_addc_u32 s3, s75, 0
	s_add_u32 s2, s2, s4
	s_addc_u32 s3, s3, 0
	global_load_dwordx4 v[148:151], v52, s[2:3]
	s_add_u32 s2, s2, 0x10000
	s_addc_u32 s3, s3, 0
	global_load_dwordx4 v[152:155], v52, s[2:3]
.Lp1n_nocol_0:
	s_add_u32 s0, s19, 1
	s_cmpk_lt_u32 s0, 0x2000
	s_cselect_b32 s2, s8, s10
	s_cselect_b32 s3, s9, s11
	s_and_b32 s1, s0, 0x1fff
	s_lshl_b32 s4, s1, 12
	s_add_u32 s2, s2, s4
	s_addc_u32 s3, s3, 0
	global_load_dwordx4 v[100:103], v52, s[2:3] offset:0 nt
	global_load_dwordx4 v[104:107], v52, s[2:3] offset:1024 nt
	global_load_dwordx4 v[108:111], v52, s[2:3] offset:2048 nt
	global_load_dwordx4 v[112:115], v52, s[2:3] offset:3072 nt
	s_cmp_eq_u32 s26, 0
	s_cbranch_scc1 .Lp1n_nocol_1
	s_and_b32 s4, s0, 63
	s_lshl_b32 s4, s4, 10
	s_add_u32 s2, s74, 0x94000
	s_addc_u32 s3, s75, 0
	s_add_u32 s2, s2, s4
	s_addc_u32 s3, s3, 0
	global_load_dwordx4 v[156:159], v52, s[2:3]
	s_add_u32 s2, s2, 0x10000
	s_addc_u32 s3, s3, 0
	global_load_dwordx4 v[160:163], v52, s[2:3]
.Lp1n_nocol_1:
	s_add_u32 s0, s19, 2
	s_cmpk_lt_u32 s0, 0x2000
	s_cselect_b32 s2, s8, s10
	s_cselect_b32 s3, s9, s11
	s_and_b32 s1, s0, 0x1fff
	s_lshl_b32 s4, s1, 12
	s_add_u32 s2, s2, s4
	s_addc_u32 s3, s3, 0
	global_load_dwordx4 v[116:119], v52, s[2:3] offset:0 nt
	global_load_dwordx4 v[120:123], v52, s[2:3] offset:1024 nt
	global_load_dwordx4 v[124:127], v52, s[2:3] offset:2048 nt
	global_load_dwordx4 v[128:131], v52, s[2:3] offset:3072 nt
	s_cmp_eq_u32 s26, 0
	s_cbranch_scc1 .Lp1n_nocol_2
	s_and_b32 s4, s0, 63
	s_lshl_b32 s4, s4, 10
	s_add_u32 s2, s74, 0x94000
	s_addc_u32 s3, s75, 0
	s_add_u32 s2, s2, s4
	s_addc_u32 s3, s3, 0
	global_load_dwordx4 v[164:167], v52, s[2:3]
	s_add_u32 s2, s2, 0x10000
	s_addc_u32 s3, s3, 0
	global_load_dwordx4 v[168:171], v52, s[2:3]
.Lp1n_nocol_2:
	s_add_u32 s0, s19, 3
	s_cmpk_lt_u32 s0, 0x2000
	s_cselect_b32 s2, s8, s10
	s_cselect_b32 s3, s9, s11
	s_and_b32 s1, s0, 0x1fff
	s_lshl_b32 s4, s1, 12
	s_add_u32 s2, s2, s4
	s_addc_u32 s3, s3, 0
	global_load_dwordx4 v[132:135], v52, s[2:3] offset:0 nt
	global_load_dwordx4 v[136:139], v52, s[2:3] offset:1024 nt
	global_load_dwordx4 v[140:143], v52, s[2:3] offset:2048 nt
	global_load_dwordx4 v[144:147], v52, s[2:3] offset:3072 nt
	s_cmp_eq_u32 s26, 0
	s_cbranch_scc1 .Lp1n_nocol_3
	s_and_b32 s4, s0, 63
	s_lshl_b32 s4, s4, 10
	s_add_u32 s2, s74, 0x94000
	s_addc_u32 s3, s75, 0
	s_add_u32 s2, s2, s4
	s_addc_u32 s3, s3, 0
	global_load_dwordx4 v[172:175], v52, s[2:3]
	s_add_u32 s2, s2, 0x10000
	s_addc_u32 s3, s3, 0
	global_load_dwordx4 v[176:179], v52, s[2:3]
.Lp1n_nocol_3:
	s_waitcnt vmcnt(0)
	s_cmp_eq_u32 s26, 0
	s_cbranch_scc1 .Lp1n_nope_0
	v_pk_add_f32 v[84:85], v[84:85], v[180:181]
	v_pk_add_f32 v[86:87], v[86:87], v[182:183]
	v_pk_add_f32 v[88:89], v[88:89], v[184:185]
	v_pk_add_f32 v[90:91], v[90:91], v[186:187]
	v_pk_add_f32 v[92:93], v[92:93], v[148:149]
	v_pk_add_f32 v[94:95], v[94:95], v[150:151]
	v_pk_add_f32 v[96:97], v[96:97], v[152:153]
	v_pk_add_f32 v[98:99], v[98:99], v[154:155]
	v_pk_add_f32 v[100:101], v[100:101], v[180:181]
	v_pk_add_f32 v[102:103], v[102:103], v[182:183]
	v_pk_add_f32 v[104:105], v[104:105], v[184:185]
	v_pk_add_f32 v[106:107], v[106:107], v[186:187]
	v_pk_add_f32 v[108:109], v[108:109], v[156:157]
	v_pk_add_f32 v[110:111], v[110:111], v[158:159]
	v_pk_add_f32 v[112:113], v[112:113], v[160:161]
	v_pk_add_f32 v[114:115], v[114:115], v[162:163]
	v_pk_add_f32 v[116:117], v[116:117], v[180:181]
	v_pk_add_f32 v[118:119], v[118:119], v[182:183]
	v_pk_add_f32 v[120:121], v[120:121], v[184:185]
	v_pk_add_f32 v[122:123], v[122:123], v[186:187]
	v_pk_add_f32 v[124:125], v[124:125], v[164:165]
	v_pk_add_f32 v[126:127], v[126:127], v[166:167]
	v_pk_add_f32 v[128:129], v[128:129], v[168:169]
	v_pk_add_f32 v[130:131], v[130:131], v[170:171]
	v_pk_add_f32 v[132:133], v[132:133], v[180:181]
	v_pk_add_f32 v[134:135], v[134:135], v[182:183]
	v_pk_add_f32 v[136:137], v[136:137], v[184:185]
	v_pk_add_f32 v[138:139], v[138:139], v[186:187]
	v_pk_add_f32 v[140:141], v[140:141], v[172:173]
	v_pk_add_f32 v[142:143], v[142:143], v[174:175]
	v_pk_add_f32 v[144:145], v[144:145], v[176:177]
	v_pk_add_f32 v[146:147], v[146:147], v[178:179]
.Lp1n_nope_0:
	v_pk_mul_f32 v[34:35], v[84:85], v[84:85]
	v_pk_mul_f32 v[36:37], v[100:101], v[100:101]
	v_pk_mul_f32 v[38:39], v[116:117], v[116:117]
	v_pk_mul_f32 v[40:41], v[132:133], v[132:133]
	v_pk_fma_f32 v[34:35], v[86:87], v[86:87], v[34:35]
	v_pk_fma_f32 v[36:37], v[102:103], v[102:103], v[36:37]
	v_pk_fma_f32 v[38:39], v[118:119], v[118:119], v[38:39]
	v_pk_fma_f32 v[40:41], v[134:135], v[134:135], v[40:41]
	v_pk_fma_f32 v[34:35], v[88:89], v[88:89], v[34:35]
	v_pk_fma_f32 v[36:37], v[104:105], v[104:105], v[36:37]
	v_pk_fma_f32 v[38:39], v[120:121], v[120:121], v[38:39]
	v_pk_fma_f32 v[40:41], v[136:137], v[136:137], v[40:41]
	v_pk_fma_f32 v[34:35], v[90:91], v[90:91], v[34:35]
	v_pk_fma_f32 v[36:37], v[106:107], v[106:107], v[36:37]
	v_pk_fma_f32 v[38:39], v[122:123], v[122:123], v[38:39]
	v_pk_fma_f32 v[40:41], v[138:139], v[138:139], v[40:41]
	v_pk_fma_f32 v[34:35], v[92:93], v[92:93], v[34:35]
	v_pk_fma_f32 v[36:37], v[108:109], v[108:109], v[36:37]
	v_pk_fma_f32 v[38:39], v[124:125], v[124:125], v[38:39]
	v_pk_fma_f32 v[40:41], v[140:141], v[140:141], v[40:41]
	v_pk_fma_f32 v[34:35], v[94:95], v[94:95], v[34:35]
	v_pk_fma_f32 v[36:37], v[110:111], v[110:111], v[36:37]
	v_pk_fma_f32 v[38:39], v[126:127], v[126:127], v[38:39]
	v_pk_fma_f32 v[40:41], v[142:143], v[142:143], v[40:41]
	v_pk_fma_f32 v[34:35], v[96:97], v[96:97], v[34:35]
	v_pk_fma_f32 v[36:37], v[112:113], v[112:113], v[36:37]
	v_pk_fma_f32 v[38:39], v[128:129], v[128:129], v[38:39]
	v_pk_fma_f32 v[40:41], v[144:145], v[144:145], v[40:41]
	v_pk_fma_f32 v[34:35], v[98:99], v[98:99], v[34:35]
	v_pk_fma_f32 v[36:37], v[114:115], v[114:115], v[36:37]
	v_pk_fma_f32 v[38:39], v[130:131], v[130:131], v[38:39]
	v_pk_fma_f32 v[40:41], v[146:147], v[146:147], v[40:41]
	v_add_f32_e32 v34, v34, v35
	v_add_f32_e32 v36, v36, v37
	v_add_f32_e32 v38, v38, v39
	v_add_f32_e32 v40, v40, v41
	ds_bpermute_b32 v35, v51, v34
	ds_bpermute_b32 v37, v51, v36
	ds_bpermute_b32 v39, v51, v38
	ds_bpermute_b32 v41, v51, v40
	s_waitcnt lgkmcnt(0)
	v_add_f32_e32 v34, v34, v35
	v_add_f32_e32 v36, v36, v37
	v_add_f32_e32 v38, v38, v39
	v_add_f32_e32 v40, v40, v41
	ds_bpermute_b32 v35, v66, v34
	ds_bpermute_b32 v37, v66, v36
	ds_bpermute_b32 v39, v66, v38
	ds_bpermute_b32 v41, v66, v40
	s_waitcnt lgkmcnt(0)
	v_add_f32_e32 v34, v34, v35
	v_add_f32_e32 v36, v36, v37
	v_add_f32_e32 v38, v38, v39
	v_add_f32_e32 v40, v40, v41
	ds_bpermute_b32 v35, v67, v34
	ds_bpermute_b32 v37, v67, v36
	ds_bpermute_b32 v39, v67, v38
	ds_bpermute_b32 v41, v67, v40
	s_waitcnt lgkmcnt(0)
	v_add_f32_e32 v34, v34, v35
	v_add_f32_e32 v36, v36, v37
	v_add_f32_e32 v38, v38, v39
	v_add_f32_e32 v40, v40, v41
	ds_bpermute_b32 v35, v68, v34
	ds_bpermute_b32 v37, v68, v36
	ds_bpermute_b32 v39, v68, v38
	ds_bpermute_b32 v41, v68, v40
	s_waitcnt lgkmcnt(0)
	v_add_f32_e32 v34, v34, v35
	v_add_f32_e32 v36, v36, v37
	v_add_f32_e32 v38, v38, v39
	v_add_f32_e32 v40, v40, v41
	ds_bpermute_b32 v35, v69, v34
	ds_bpermute_b32 v37, v69, v36
	ds_bpermute_b32 v39, v69, v38
	ds_bpermute_b32 v41, v69, v40
	s_waitcnt lgkmcnt(0)
	v_add_f32_e32 v34, v34, v35
	v_add_f32_e32 v36, v36, v37
	v_add_f32_e32 v38, v38, v39
	v_add_f32_e32 v40, v40, v41
	ds_bpermute_b32 v35, v70, v34
	ds_bpermute_b32 v37, v70, v36
	ds_bpermute_b32 v39, v70, v38
	ds_bpermute_b32 v41, v70, v40
	s_waitcnt lgkmcnt(0)
	v_add_f32_e32 v34, v34, v35
	v_add_f32_e32 v36, v36, v37
	v_add_f32_e32 v38, v38, v39
	v_add_f32_e32 v40, v40, v41
	v_fmamk_f32 v34, v34, 0x3a800000, v74
	v_fmamk_f32 v36, v36, 0x3a800000, v74
	v_fmamk_f32 v38, v38, 0x3a800000, v74
	v_fmamk_f32 v40, v40, 0x3a800000, v74
	v_mul_f32_e32 v75, 0x4b800000, v34
	v_cmp_gt_f32_e32 vcc, s24, v34
	s_nop 1
	v_cndmask_b32_e32 v34, v34, v75, vcc
	v_rsq_f32_e32 v34, v34
	s_nop 0
	v_mul_f32_e32 v75, 0x45800000, v34
	v_cndmask_b32_e32 v34, v34, v75, vcc
	v_mov_b32_e32 v35, 0
	v_mul_f32_e32 v75, 0x4b800000, v36
	v_cmp_gt_f32_e32 vcc, s24, v36
	s_nop 1
	v_cndmask_b32_e32 v36, v36, v75, vcc
	v_rsq_f32_e32 v36, v36
	s_nop 0
	v_mul_f32_e32 v75, 0x45800000, v36
	v_cndmask_b32_e32 v36, v36, v75, vcc
	v_mov_b32_e32 v37, 0
	v_mul_f32_e32 v75, 0x4b800000, v38
	v_cmp_gt_f32_e32 vcc, s24, v38
	s_nop 1
	v_cndmask_b32_e32 v38, v38, v75, vcc
	v_rsq_f32_e32 v38, v38
	s_nop 0
	v_mul_f32_e32 v75, 0x45800000, v38
	v_cndmask_b32_e32 v38, v38, v75, vcc
	v_mov_b32_e32 v39, 0
	v_mul_f32_e32 v75, 0x4b800000, v40
	v_cmp_gt_f32_e32 vcc, s24, v40
	s_nop 1
	v_cndmask_b32_e32 v40, v40, v75, vcc
	v_rsq_f32_e32 v40, v40
	s_nop 0
	v_mul_f32_e32 v75, 0x45800000, v40
	v_cndmask_b32_e32 v40, v40, v75, vcc
	v_mov_b32_e32 v41, 0
	s_add_u32 s0, s19, 0
	s_lshl_b32 s0, s0, 11
	s_add_u32 s2, s72, s0
	s_addc_u32 s3, s73, 0
	v_pk_mul_f32 v[84:85], v[84:85], v[34:35] op_sel_hi:[1,0]
	v_pk_mul_f32 v[86:87], v[86:87], v[34:35] op_sel_hi:[1,0]
	v_pk_fma_f32 v[84:85], v[2:3], v[84:85], v[10:11]
	v_pk_fma_f32 v[86:87], v[4:5], v[86:87], v[12:13]
	v_cvt_pk_bf16_f32 v84, v84, v85
	v_cvt_pk_bf16_f32 v85, v86, v87
	global_store_dwordx2 v78, v[84:85], s[2:3] offset:0
	v_pk_mul_f32 v[88:89], v[88:89], v[34:35] op_sel_hi:[1,0]
	v_pk_mul_f32 v[90:91], v[90:91], v[34:35] op_sel_hi:[1,0]
	v_pk_fma_f32 v[88:89], v[6:7], v[88:89], v[14:15]
	v_pk_fma_f32 v[90:91], v[8:9], v[90:91], v[16:17]
	v_cvt_pk_bf16_f32 v88, v88, v89
	v_cvt_pk_bf16_f32 v89, v90, v91
	global_store_dwordx2 v78, v[88:89], s[2:3] offset:512
	v_pk_mul_f32 v[92:93], v[92:93], v[34:35] op_sel_hi:[1,0]
	v_pk_mul_f32 v[94:95], v[94:95], v[34:35] op_sel_hi:[1,0]
	v_pk_fma_f32 v[92:93], v[18:19], v[92:93], v[26:27]
	v_pk_fma_f32 v[94:95], v[20:21], v[94:95], v[28:29]
	v_cvt_pk_bf16_f32 v92, v92, v93
	v_cvt_pk_bf16_f32 v93, v94, v95
	global_store_dwordx2 v78, v[92:93], s[2:3] offset:1024
	v_pk_mul_f32 v[96:97], v[96:97], v[34:35] op_sel_hi:[1,0]
	v_pk_mul_f32 v[98:99], v[98:99], v[34:35] op_sel_hi:[1,0]
	v_pk_fma_f32 v[96:97], v[22:23], v[96:97], v[30:31]
	v_pk_fma_f32 v[98:99], v[24:25], v[98:99], v[32:33]
	v_cvt_pk_bf16_f32 v96, v96, v97
	v_cvt_pk_bf16_f32 v97, v98, v99
	global_store_dwordx2 v78, v[96:97], s[2:3] offset:1536
	s_add_u32 s0, s19, 1
	s_lshl_b32 s0, s0, 11
	s_add_u32 s2, s72, s0
	s_addc_u32 s3, s73, 0
	v_pk_mul_f32 v[100:101], v[100:101], v[36:37] op_sel_hi:[1,0]
	v_pk_mul_f32 v[102:103], v[102:103], v[36:37] op_sel_hi:[1,0]
	v_pk_fma_f32 v[100:101], v[2:3], v[100:101], v[10:11]
	v_pk_fma_f32 v[102:103], v[4:5], v[102:103], v[12:13]
	v_cvt_pk_bf16_f32 v100, v100, v101
	v_cvt_pk_bf16_f32 v101, v102, v103
	global_store_dwordx2 v78, v[100:101], s[2:3] offset:0
	v_pk_mul_f32 v[104:105], v[104:105], v[36:37] op_sel_hi:[1,0]
	v_pk_mul_f32 v[106:107], v[106:107], v[36:37] op_sel_hi:[1,0]
	v_pk_fma_f32 v[104:105], v[6:7], v[104:105], v[14:15]
	v_pk_fma_f32 v[106:107], v[8:9], v[106:107], v[16:17]
	v_cvt_pk_bf16_f32 v104, v104, v105
	v_cvt_pk_bf16_f32 v105, v106, v107
	global_store_dwordx2 v78, v[104:105], s[2:3] offset:512
	v_pk_mul_f32 v[108:109], v[108:109], v[36:37] op_sel_hi:[1,0]
	v_pk_mul_f32 v[110:111], v[110:111], v[36:37] op_sel_hi:[1,0]
	v_pk_fma_f32 v[108:109], v[18:19], v[108:109], v[26:27]
	v_pk_fma_f32 v[110:111], v[20:21], v[110:111], v[28:29]
	v_cvt_pk_bf16_f32 v108, v108, v109
	v_cvt_pk_bf16_f32 v109, v110, v111
	global_store_dwordx2 v78, v[108:109], s[2:3] offset:1024
	v_pk_mul_f32 v[112:113], v[112:113], v[36:37] op_sel_hi:[1,0]
	v_pk_mul_f32 v[114:115], v[114:115], v[36:37] op_sel_hi:[1,0]
	v_pk_fma_f32 v[112:113], v[22:23], v[112:113], v[30:31]
	v_pk_fma_f32 v[114:115], v[24:25], v[114:115], v[32:33]
	v_cvt_pk_bf16_f32 v112, v112, v113
	v_cvt_pk_bf16_f32 v113, v114, v115
	global_store_dwordx2 v78, v[112:113], s[2:3] offset:1536
	s_add_u32 s0, s19, 2
	s_lshl_b32 s0, s0, 11
	s_add_u32 s2, s72, s0
	s_addc_u32 s3, s73, 0
	v_pk_mul_f32 v[116:117], v[116:117], v[38:39] op_sel_hi:[1,0]
	v_pk_mul_f32 v[118:119], v[118:119], v[38:39] op_sel_hi:[1,0]
	v_pk_fma_f32 v[116:117], v[2:3], v[116:117], v[10:11]
	v_pk_fma_f32 v[118:119], v[4:5], v[118:119], v[12:13]
	v_cvt_pk_bf16_f32 v116, v116, v117
	v_cvt_pk_bf16_f32 v117, v118, v119
	global_store_dwordx2 v78, v[116:117], s[2:3] offset:0
	v_pk_mul_f32 v[120:121], v[120:121], v[38:39] op_sel_hi:[1,0]
	v_pk_mul_f32 v[122:123], v[122:123], v[38:39] op_sel_hi:[1,0]
	v_pk_fma_f32 v[120:121], v[6:7], v[120:121], v[14:15]
	v_pk_fma_f32 v[122:123], v[8:9], v[122:123], v[16:17]
	v_cvt_pk_bf16_f32 v120, v120, v121
	v_cvt_pk_bf16_f32 v121, v122, v123
	global_store_dwordx2 v78, v[120:121], s[2:3] offset:512
	v_pk_mul_f32 v[124:125], v[124:125], v[38:39] op_sel_hi:[1,0]
	v_pk_mul_f32 v[126:127], v[126:127], v[38:39] op_sel_hi:[1,0]
	v_pk_fma_f32 v[124:125], v[18:19], v[124:125], v[26:27]
	v_pk_fma_f32 v[126:127], v[20:21], v[126:127], v[28:29]
	v_cvt_pk_bf16_f32 v124, v124, v125
	v_cvt_pk_bf16_f32 v125, v126, v127
	global_store_dwordx2 v78, v[124:125], s[2:3] offset:1024
	v_pk_mul_f32 v[128:129], v[128:129], v[38:39] op_sel_hi:[1,0]
	v_pk_mul_f32 v[130:131], v[130:131], v[38:39] op_sel_hi:[1,0]
	v_pk_fma_f32 v[128:129], v[22:23], v[128:129], v[30:31]
	v_pk_fma_f32 v[130:131], v[24:25], v[130:131], v[32:33]
	v_cvt_pk_bf16_f32 v128, v128, v129
	v_cvt_pk_bf16_f32 v129, v130, v131
	global_store_dwordx2 v78, v[128:129], s[2:3] offset:1536
	s_add_u32 s0, s19, 3
	s_lshl_b32 s0, s0, 11
	s_add_u32 s2, s72, s0
	s_addc_u32 s3, s73, 0
	v_pk_mul_f32 v[132:133], v[132:133], v[40:41] op_sel_hi:[1,0]
	v_pk_mul_f32 v[134:135], v[134:135], v[40:41] op_sel_hi:[1,0]
	v_pk_fma_f32 v[132:133], v[2:3], v[132:133], v[10:11]
	v_pk_fma_f32 v[134:135], v[4:5], v[134:135], v[12:13]
	v_cvt_pk_bf16_f32 v132, v132, v133
	v_cvt_pk_bf16_f32 v133, v134, v135
	global_store_dwordx2 v78, v[132:133], s[2:3] offset:0
	v_pk_mul_f32 v[136:137], v[136:137], v[40:41] op_sel_hi:[1,0]
	v_pk_mul_f32 v[138:139], v[138:139], v[40:41] op_sel_hi:[1,0]
	v_pk_fma_f32 v[136:137], v[6:7], v[136:137], v[14:15]
	v_pk_fma_f32 v[138:139], v[8:9], v[138:139], v[16:17]
	v_cvt_pk_bf16_f32 v136, v136, v137
	v_cvt_pk_bf16_f32 v137, v138, v139
	global_store_dwordx2 v78, v[136:137], s[2:3] offset:512
	v_pk_mul_f32 v[140:141], v[140:141], v[40:41] op_sel_hi:[1,0]
	v_pk_mul_f32 v[142:143], v[142:143], v[40:41] op_sel_hi:[1,0]
	v_pk_fma_f32 v[140:141], v[18:19], v[140:141], v[26:27]
	v_pk_fma_f32 v[142:143], v[20:21], v[142:143], v[28:29]
	v_cvt_pk_bf16_f32 v140, v140, v141
	v_cvt_pk_bf16_f32 v141, v142, v143
	global_store_dwordx2 v78, v[140:141], s[2:3] offset:1024
	v_pk_mul_f32 v[144:145], v[144:145], v[40:41] op_sel_hi:[1,0]
	v_pk_mul_f32 v[146:147], v[146:147], v[40:41] op_sel_hi:[1,0]
	v_pk_fma_f32 v[144:145], v[22:23], v[144:145], v[30:31]
	v_pk_fma_f32 v[146:147], v[24:25], v[146:147], v[32:33]
	v_cvt_pk_bf16_f32 v144, v144, v145
	v_cvt_pk_bf16_f32 v145, v146, v147
	global_store_dwordx2 v78, v[144:145], s[2:3] offset:1536
	s_nop 1
	s_add_u32 s0, s19, 4
	s_cmpk_lt_u32 s0, 0x2000
	s_cselect_b32 s2, s8, s10
	s_cselect_b32 s3, s9, s11
	s_and_b32 s1, s0, 0x1fff
	s_lshl_b32 s4, s1, 12
	s_add_u32 s2, s2, s4
	s_addc_u32 s3, s3, 0
	global_load_dwordx4 v[84:87], v52, s[2:3] offset:0 nt
	global_load_dwordx4 v[88:91], v52, s[2:3] offset:1024 nt
	global_load_dwordx4 v[92:95], v52, s[2:3] offset:2048 nt
	global_load_dwordx4 v[96:99], v52, s[2:3] offset:3072 nt
	s_cmp_eq_u32 s26, 0
	s_cbranch_scc1 .Lp1n_nocol_4
	s_and_b32 s4, s0, 63
	s_lshl_b32 s4, s4, 10
	s_add_u32 s2, s74, 0x94000
	s_addc_u32 s3, s75, 0
	s_add_u32 s2, s2, s4
	s_addc_u32 s3, s3, 0
	global_load_dwordx4 v[148:151], v52, s[2:3]
	s_add_u32 s2, s2, 0x10000
	s_addc_u32 s3, s3, 0
	global_load_dwordx4 v[152:155], v52, s[2:3]
.Lp1n_nocol_4:
	s_add_u32 s0, s19, 5
	s_cmpk_lt_u32 s0, 0x2000
	s_cselect_b32 s2, s8, s10
	s_cselect_b32 s3, s9, s11
	s_and_b32 s1, s0, 0x1fff
	s_lshl_b32 s4, s1, 12
	s_add_u32 s2, s2, s4
	s_addc_u32 s3, s3, 0
	global_load_dwordx4 v[100:103], v52, s[2:3] offset:0 nt
	global_load_dwordx4 v[104:107], v52, s[2:3] offset:1024 nt
	global_load_dwordx4 v[108:111], v52, s[2:3] offset:2048 nt
	global_load_dwordx4 v[112:115], v52, s[2:3] offset:3072 nt
	s_cmp_eq_u32 s26, 0
	s_cbranch_scc1 .Lp1n_nocol_5
	s_and_b32 s4, s0, 63
	s_lshl_b32 s4, s4, 10
	s_add_u32 s2, s74, 0x94000
	s_addc_u32 s3, s75, 0
	s_add_u32 s2, s2, s4
	s_addc_u32 s3, s3, 0
	global_load_dwordx4 v[156:159], v52, s[2:3]
	s_add_u32 s2, s2, 0x10000
	s_addc_u32 s3, s3, 0
	global_load_dwordx4 v[160:163], v52, s[2:3]
.Lp1n_nocol_5:
	s_add_u32 s0, s19, 6
	s_cmpk_lt_u32 s0, 0x2000
	s_cselect_b32 s2, s8, s10
	s_cselect_b32 s3, s9, s11
	s_and_b32 s1, s0, 0x1fff
	s_lshl_b32 s4, s1, 12
	s_add_u32 s2, s2, s4
	s_addc_u32 s3, s3, 0
	global_load_dwordx4 v[116:119], v52, s[2:3] offset:0 nt
	global_load_dwordx4 v[120:123], v52, s[2:3] offset:1024 nt
	global_load_dwordx4 v[124:127], v52, s[2:3] offset:2048 nt
	global_load_dwordx4 v[128:131], v52, s[2:3] offset:3072 nt
	s_cmp_eq_u32 s26, 0
	s_cbranch_scc1 .Lp1n_nocol_6
	s_and_b32 s4, s0, 63
	s_lshl_b32 s4, s4, 10
	s_add_u32 s2, s74, 0x94000
	s_addc_u32 s3, s75, 0
	s_add_u32 s2, s2, s4
	s_addc_u32 s3, s3, 0
	global_load_dwordx4 v[164:167], v52, s[2:3]
	s_add_u32 s2, s2, 0x10000
	s_addc_u32 s3, s3, 0
	global_load_dwordx4 v[168:171], v52, s[2:3]
.Lp1n_nocol_6:
	s_add_u32 s0, s19, 7
	s_cmpk_lt_u32 s0, 0x2000
	s_cselect_b32 s2, s8, s10
	s_cselect_b32 s3, s9, s11
	s_and_b32 s1, s0, 0x1fff
	s_lshl_b32 s4, s1, 12
	s_add_u32 s2, s2, s4
	s_addc_u32 s3, s3, 0
	global_load_dwordx4 v[132:135], v52, s[2:3] offset:0 nt
	global_load_dwordx4 v[136:139], v52, s[2:3] offset:1024 nt
	global_load_dwordx4 v[140:143], v52, s[2:3] offset:2048 nt
	global_load_dwordx4 v[144:147], v52, s[2:3] offset:3072 nt
	s_cmp_eq_u32 s26, 0
	s_cbranch_scc1 .Lp1n_nocol_7
	s_and_b32 s4, s0, 63
	s_lshl_b32 s4, s4, 10
	s_add_u32 s2, s74, 0x94000
	s_addc_u32 s3, s75, 0
	s_add_u32 s2, s2, s4
	s_addc_u32 s3, s3, 0
	global_load_dwordx4 v[172:175], v52, s[2:3]
	s_add_u32 s2, s2, 0x10000
	s_addc_u32 s3, s3, 0
	global_load_dwordx4 v[176:179], v52, s[2:3]

.Lp1n_nope_1:
	v_pk_mul_f32 v[34:35], v[84:85], v[84:85]
	v_pk_mul_f32 v[36:37], v[100:101], v[100:101]
	v_pk_mul_f32 v[38:39], v[116:117], v[116:117]
	v_pk_mul_f32 v[40:41], v[132:133], v[132:133]
	v_pk_fma_f32 v[34:35], v[86:87], v[86:87], v[34:35]
	v_pk_fma_f32 v[36:37], v[102:103], v[102:103], v[36:37]
	v_pk_fma_f32 v[38:39], v[118:119], v[118:119], v[38:39]
	v_pk_fma_f32 v[40:41], v[134:135], v[134:135], v[40:41]
	v_pk_fma_f32 v[34:35], v[88:89], v[88:89], v[34:35]
	v_pk_fma_f32 v[36:37], v[104:105], v[104:105], v[36:37]
	v_pk_fma_f32 v[38:39], v[120:121], v[120:121], v[38:39]
	v_pk_fma_f32 v[40:41], v[136:137], v[136:137], v[40:41]
	v_pk_fma_f32 v[34:35], v[90:91], v[90:91], v[34:35]
	v_pk_fma_f32 v[36:37], v[106:107], v[106:107], v[36:37]
	v_pk_fma_f32 v[38:39], v[122:123], v[122:123], v[38:39]
	v_pk_fma_f32 v[40:41], v[138:139], v[138:139], v[40:41]
	v_pk_fma_f32 v[34:35], v[92:93], v[92:93], v[34:35]
	v_pk_fma_f32 v[36:37], v[108:109], v[108:109], v[36:37]
	v_pk_fma_f32 v[38:39], v[124:125], v[124:125], v[38:39]
	v_pk_fma_f32 v[40:41], v[140:141], v[140:141], v[40:41]
	v_pk_fma_f32 v[34:35], v[94:95], v[94:95], v[34:35]
	v_pk_fma_f32 v[36:37], v[110:111], v[110:111], v[36:37]
	v_pk_fma_f32 v[38:39], v[126:127], v[126:127], v[38:39]
	v_pk_fma_f32 v[40:41], v[142:143], v[142:143], v[40:41]
	v_pk_fma_f32 v[34:35], v[96:97], v[96:97], v[34:35]
	v_pk_fma_f32 v[36:37], v[112:113], v[112:113], v[36:37]
	v_pk_fma_f32 v[38:39], v[128:129], v[128:129], v[38:39]
	v_pk_fma_f32 v[40:41], v[144:145], v[144:145], v[40:41]
	v_pk_fma_f32 v[34:35], v[98:99], v[98:99], v[34:35]
	v_pk_fma_f32 v[36:37], v[114:115], v[114:115], v[36:37]
	v_pk_fma_f32 v[38:39], v[130:131], v[130:131], v[38:39]
	v_pk_fma_f32 v[40:41], v[146:147], v[146:147], v[40:41]
	v_add_f32_e32 v34, v34, v35
	v_add_f32_e32 v36, v36, v37
	v_add_f32_e32 v38, v38, v39
	v_add_f32_e32 v40, v40, v41
	ds_bpermute_b32 v35, v51, v34
	ds_bpermute_b32 v37, v51, v36
	ds_bpermute_b32 v39, v51, v38
	ds_bpermute_b32 v41, v51, v40
	s_waitcnt lgkmcnt(0)
	v_add_f32_e32 v34, v34, v35
	v_add_f32_e32 v36, v36, v37
	v_add_f32_e32 v38, v38, v39
	v_add_f32_e32 v40, v40, v41
	ds_bpermute_b32 v35, v66, v34
	ds_bpermute_b32 v37, v66, v36
	ds_bpermute_b32 v39, v66, v38
	ds_bpermute_b32 v41, v66, v40
	s_waitcnt lgkmcnt(0)
	v_add_f32_e32 v34, v34, v35
	v_add_f32_e32 v36, v36, v37
	v_add_f32_e32 v38, v38, v39
	v_add_f32_e32 v40, v40, v41
	ds_bpermute_b32 v35, v67, v34
	ds_bpermute_b32 v37, v67, v36
	ds_bpermute_b32 v39, v67, v38
	ds_bpermute_b32 v41, v67, v40
	s_waitcnt lgkmcnt(0)
	v_add_f32_e32 v34, v34, v35
	v_add_f32_e32 v36, v36, v37
	v_add_f32_e32 v38, v38, v39
	v_add_f32_e32 v40, v40, v41
	ds_bpermute_b32 v35, v68, v34
	ds_bpermute_b32 v37, v68, v36
	ds_bpermute_b32 v39, v68, v38
	ds_bpermute_b32 v41, v68, v40
	s_waitcnt lgkmcnt(0)
	v_add_f32_e32 v34, v34, v35
	v_add_f32_e32 v36, v36, v37
	v_add_f32_e32 v38, v38, v39
	v_add_f32_e32 v40, v40, v41
	ds_bpermute_b32 v35, v69, v34
	ds_bpermute_b32 v37, v69, v36
	ds_bpermute_b32 v39, v69, v38
	ds_bpermute_b32 v41, v69, v40
	s_waitcnt lgkmcnt(0)
	v_add_f32_e32 v34, v34, v35
	v_add_f32_e32 v36, v36, v37
	v_add_f32_e32 v38, v38, v39
	v_add_f32_e32 v40, v40, v41
	ds_bpermute_b32 v35, v70, v34
	ds_bpermute_b32 v37, v70, v36
	ds_bpermute_b32 v39, v70, v38
	ds_bpermute_b32 v41, v70, v40
	s_waitcnt lgkmcnt(0)
	v_add_f32_e32 v34, v34, v35
	v_add_f32_e32 v36, v36, v37
	v_add_f32_e32 v38, v38, v39
	v_add_f32_e32 v40, v40, v41
	v_fmamk_f32 v34, v34, 0x3a800000, v74
	v_fmamk_f32 v36, v36, 0x3a800000, v74
	v_fmamk_f32 v38, v38, 0x3a800000, v74
	v_fmamk_f32 v40, v40, 0x3a800000, v74
	v_mul_f32_e32 v75, 0x4b800000, v34
	v_cmp_gt_f32_e32 vcc, s24, v34
	s_nop 1
	v_cndmask_b32_e32 v34, v34, v75, vcc
	v_rsq_f32_e32 v34, v34
	s_nop 0
	v_mul_f32_e32 v75, 0x45800000, v34
	v_cndmask_b32_e32 v34, v34, v75, vcc
	v_mov_b32_e32 v35, 0
	v_mul_f32_e32 v75, 0x4b800000, v36
	v_cmp_gt_f32_e32 vcc, s24, v36
	s_nop 1
	v_cndmask_b32_e32 v36, v36, v75, vcc
	v_rsq_f32_e32 v36, v36
	s_nop 0
	v_mul_f32_e32 v75, 0x45800000, v36
	v_cndmask_b32_e32 v36, v36, v75, vcc
	v_mov_b32_e32 v37, 0
	v_mul_f32_e32 v75, 0x4b800000, v38
	v_cmp_gt_f32_e32 vcc, s24, v38
	s_nop 1
	v_cndmask_b32_e32 v38, v38, v75, vcc
	v_rsq_f32_e32 v38, v38
	s_nop 0
	v_mul_f32_e32 v75, 0x45800000, v38
	v_cndmask_b32_e32 v38, v38, v75, vcc
	v_mov_b32_e32 v39, 0
	v_mul_f32_e32 v75, 0x4b800000, v40
	v_cmp_gt_f32_e32 vcc, s24, v40
	s_nop 1
	v_cndmask_b32_e32 v40, v40, v75, vcc
	v_rsq_f32_e32 v40, v40
	s_nop 0
	v_mul_f32_e32 v75, 0x45800000, v40
	v_cndmask_b32_e32 v40, v40, v75, vcc
	v_mov_b32_e32 v41, 0
	s_add_u32 s0, s19, 4
	s_lshl_b32 s0, s0, 11
	s_add_u32 s2, s72, s0
	s_addc_u32 s3, s73, 0
	v_pk_mul_f32 v[84:85], v[84:85], v[34:35] op_sel_hi:[1,0]
	v_pk_mul_f32 v[86:87], v[86:87], v[34:35] op_sel_hi:[1,0]
	v_pk_fma_f32 v[84:85], v[2:3], v[84:85], v[10:11]
	v_pk_fma_f32 v[86:87], v[4:5], v[86:87], v[12:13]
	v_cvt_pk_bf16_f32 v84, v84, v85
	v_cvt_pk_bf16_f32 v85, v86, v87
	global_store_dwordx2 v78, v[84:85], s[2:3] offset:0
	v_pk_mul_f32 v[88:89], v[88:89], v[34:35] op_sel_hi:[1,0]
	v_pk_mul_f32 v[90:91], v[90:91], v[34:35] op_sel_hi:[1,0]
	v_pk_fma_f32 v[88:89], v[6:7], v[88:89], v[14:15]
	v_pk_fma_f32 v[90:91], v[8:9], v[90:91], v[16:17]
	v_cvt_pk_bf16_f32 v88, v88, v89
	v_cvt_pk_bf16_f32 v89, v90, v91
	global_store_dwordx2 v78, v[88:89], s[2:3] offset:512
	v_pk_mul_f32 v[92:93], v[92:93], v[34:35] op_sel_hi:[1,0]
	v_pk_mul_f32 v[94:95], v[94:95], v[34:35] op_sel_hi:[1,0]
	v_pk_fma_f32 v[92:93], v[18:19], v[92:93], v[26:27]
	v_pk_fma_f32 v[94:95], v[20:21], v[94:95], v[28:29]
	v_cvt_pk_bf16_f32 v92, v92, v93
	v_cvt_pk_bf16_f32 v93, v94, v95
	global_store_dwordx2 v78, v[92:93], s[2:3] offset:1024
	v_pk_mul_f32 v[96:97], v[96:97], v[34:35] op_sel_hi:[1,0]
	v_pk_mul_f32 v[98:99], v[98:99], v[34:35] op_sel_hi:[1,0]
	v_pk_fma_f32 v[96:97], v[22:23], v[96:97], v[30:31]
	v_pk_fma_f32 v[98:99], v[24:25], v[98:99], v[32:33]
	v_cvt_pk_bf16_f32 v96, v96, v97
	v_cvt_pk_bf16_f32 v97, v98, v99
	global_store_dwordx2 v78, v[96:97], s[2:3] offset:1536
	s_add_u32 s0, s19, 5
	s_lshl_b32 s0, s0, 11
	s_add_u32 s2, s72, s0
	s_addc_u32 s3, s73, 0
	v_pk_mul_f32 v[100:101], v[100:101], v[36:37] op_sel_hi:[1,0]
	v_pk_mul_f32 v[102:103], v[102:103], v[36:37] op_sel_hi:[1,0]
	v_pk_fma_f32 v[100:101], v[2:3], v[100:101], v[10:11]
	v_pk_fma_f32 v[102:103], v[4:5], v[102:103], v[12:13]
	v_cvt_pk_bf16_f32 v100, v100, v101
	v_cvt_pk_bf16_f32 v101, v102, v103
	global_store_dwordx2 v78, v[100:101], s[2:3] offset:0
	v_pk_mul_f32 v[104:105], v[104:105], v[36:37] op_sel_hi:[1,0]
	v_pk_mul_f32 v[106:107], v[106:107], v[36:37] op_sel_hi:[1,0]
	v_pk_fma_f32 v[104:105], v[6:7], v[104:105], v[14:15]
	v_pk_fma_f32 v[106:107], v[8:9], v[106:107], v[16:17]
	v_cvt_pk_bf16_f32 v104, v104, v105
	v_cvt_pk_bf16_f32 v105, v106, v107
	global_store_dwordx2 v78, v[104:105], s[2:3] offset:512
	v_pk_mul_f32 v[108:109], v[108:109], v[36:37] op_sel_hi:[1,0]
	v_pk_mul_f32 v[110:111], v[110:111], v[36:37] op_sel_hi:[1,0]
	v_pk_fma_f32 v[108:109], v[18:19], v[108:109], v[26:27]
	v_pk_fma_f32 v[110:111], v[20:21], v[110:111], v[28:29]
	v_cvt_pk_bf16_f32 v108, v108, v109
	v_cvt_pk_bf16_f32 v109, v110, v111
	global_store_dwordx2 v78, v[108:109], s[2:3] offset:1024
	v_pk_mul_f32 v[112:113], v[112:113], v[36:37] op_sel_hi:[1,0]
	v_pk_mul_f32 v[114:115], v[114:115], v[36:37] op_sel_hi:[1,0]
	v_pk_fma_f32 v[112:113], v[22:23], v[112:113], v[30:31]
	v_pk_fma_f32 v[114:115], v[24:25], v[114:115], v[32:33]
	v_cvt_pk_bf16_f32 v112, v112, v113
	v_cvt_pk_bf16_f32 v113, v114, v115
	global_store_dwordx2 v78, v[112:113], s[2:3] offset:1536
	s_add_u32 s0, s19, 6
	s_lshl_b32 s0, s0, 11
	s_add_u32 s2, s72, s0
	s_addc_u32 s3, s73, 0
	v_pk_mul_f32 v[116:117], v[116:117], v[38:39] op_sel_hi:[1,0]
	v_pk_mul_f32 v[118:119], v[118:119], v[38:39] op_sel_hi:[1,0]
	v_pk_fma_f32 v[116:117], v[2:3], v[116:117], v[10:11]
	v_pk_fma_f32 v[118:119], v[4:5], v[118:119], v[12:13]
	v_cvt_pk_bf16_f32 v116, v116, v117
	v_cvt_pk_bf16_f32 v117, v118, v119
	global_store_dwordx2 v78, v[116:117], s[2:3] offset:0
	v_pk_mul_f32 v[120:121], v[120:121], v[38:39] op_sel_hi:[1,0]
	v_pk_mul_f32 v[122:123], v[122:123], v[38:39] op_sel_hi:[1,0]
	v_pk_fma_f32 v[120:121], v[6:7], v[120:121], v[14:15]
	v_pk_fma_f32 v[122:123], v[8:9], v[122:123], v[16:17]
	v_cvt_pk_bf16_f32 v120, v120, v121
	v_cvt_pk_bf16_f32 v121, v122, v123
	global_store_dwordx2 v78, v[120:121], s[2:3] offset:512
	v_pk_mul_f32 v[124:125], v[124:125], v[38:39] op_sel_hi:[1,0]
	v_pk_mul_f32 v[126:127], v[126:127], v[38:39] op_sel_hi:[1,0]
	v_pk_fma_f32 v[124:125], v[18:19], v[124:125], v[26:27]
	v_pk_fma_f32 v[126:127], v[20:21], v[126:127], v[28:29]
	v_cvt_pk_bf16_f32 v124, v124, v125
	v_cvt_pk_bf16_f32 v125, v126, v127
	global_store_dwordx2 v78, v[124:125], s[2:3] offset:1024
	v_pk_mul_f32 v[128:129], v[128:129], v[38:39] op_sel_hi:[1,0]
	v_pk_mul_f32 v[130:131], v[130:131], v[38:39] op_sel_hi:[1,0]
	v_pk_fma_f32 v[128:129], v[22:23], v[128:129], v[30:31]
	v_pk_fma_f32 v[130:131], v[24:25], v[130:131], v[32:33]
	v_cvt_pk_bf16_f32 v128, v128, v129
	v_cvt_pk_bf16_f32 v129, v130, v131
	global_store_dwordx2 v78, v[128:129], s[2:3] offset:1536
	s_add_u32 s0, s19, 7
	s_lshl_b32 s0, s0, 11
	s_add_u32 s2, s72, s0
	s_addc_u32 s3, s73, 0
	v_pk_mul_f32 v[132:133], v[132:133], v[40:41] op_sel_hi:[1,0]
	v_pk_mul_f32 v[134:135], v[134:135], v[40:41] op_sel_hi:[1,0]
	v_pk_fma_f32 v[132:133], v[2:3], v[132:133], v[10:11]
	v_pk_fma_f32 v[134:135], v[4:5], v[134:135], v[12:13]
	v_cvt_pk_bf16_f32 v132, v132, v133
	v_cvt_pk_bf16_f32 v133, v134, v135
	global_store_dwordx2 v78, v[132:133], s[2:3] offset:0
	v_pk_mul_f32 v[136:137], v[136:137], v[40:41] op_sel_hi:[1,0]
	v_pk_mul_f32 v[138:139], v[138:139], v[40:41] op_sel_hi:[1,0]
	v_pk_fma_f32 v[136:137], v[6:7], v[136:137], v[14:15]
	v_pk_fma_f32 v[138:139], v[8:9], v[138:139], v[16:17]
	v_cvt_pk_bf16_f32 v136, v136, v137
	v_cvt_pk_bf16_f32 v137, v138, v139
	global_store_dwordx2 v78, v[136:137], s[2:3] offset:512
	v_pk_mul_f32 v[140:141], v[140:141], v[40:41] op_sel_hi:[1,0]
	v_pk_mul_f32 v[142:143], v[142:143], v[40:41] op_sel_hi:[1,0]
	v_pk_fma_f32 v[140:141], v[18:19], v[140:141], v[26:27]
	v_pk_fma_f32 v[142:143], v[20:21], v[142:143], v[28:29]
	v_cvt_pk_bf16_f32 v140, v140, v141
	v_cvt_pk_bf16_f32 v141, v142, v143
	global_store_dwordx2 v78, v[140:141], s[2:3] offset:1024
	v_pk_mul_f32 v[144:145], v[144:145], v[40:41] op_sel_hi:[1,0]
	v_pk_mul_f32 v[146:147], v[146:147], v[40:41] op_sel_hi:[1,0]
	v_pk_fma_f32 v[144:145], v[22:23], v[144:145], v[30:31]
	v_pk_fma_f32 v[146:147], v[24:25], v[146:147], v[32:33]
	v_cvt_pk_bf16_f32 v144, v144, v145
	v_cvt_pk_bf16_f32 v145, v146, v147
	global_store_dwordx2 v78, v[144:145], s[2:3] offset:1536
	s_nop 1
	s_branch .LBB0_153

.Lp4n_tab:
	v_mbcnt_lo_u32_b32 v229, -1, 0
	v_mbcnt_hi_u32_b32 v229, -1, v229
	v_and_b32_e32 v230, s61, v229
	v_lshrrev_b32_e32 v231, s62, v229
	v_lshrrev_b32_e32 v232, 1, v231
	v_add_u32_e32 v232, s59, v232
	v_and_b32_e32 v232, 7, v232
	v_add_u32_e32 v233, s60, v231
	v_and_b32_e32 v233, 1, v233
	v_sub_u32_e32 v234, s61, v230
	v_cmp_eq_u32_e32 vcc, 1, v233
	s_nop 1
	v_cndmask_b32_e32 v235, v230, v234, vcc
	v_add_u32_e32 v235, s64, v235
	v_cmp_eq_u32_e32 vcc, s61, v230
	s_nop 1
	v_cndmask_b32_e64 v236, 0, 1, vcc
	v_lshlrev_b32_e32 v237, 9, v232
	v_or_b32_e32 v220, v235, v237
	v_lshlrev_b32_e32 v237, 12, v233
	v_or_b32_e32 v220, v220, v237
	s_lshl_b32 s45, s57, 13
	s_lshl_b32 s46, s58, 15
	s_or_b32 s45, s45, s46
	s_lshl_b32 s46, s63, 20
	s_or_b32 s45, s45, s46
	v_or_b32_e32 v220, s45, v220
	v_lshlrev_b32_e32 v237, 21, v236
	v_or_b32_e32 v220, v220, v237
	v_lshlrev_b32_e32 v237, 22, v230
	v_or_b32_e32 v220, v220, v237
	v_lshl_add_u32 v237, v235, 3, v232
	v_lshlrev_b32_e32 v221, 14, v237
	v_lshlrev_b32_e32 v238, 8, v233
	v_lshl_add_u32 v224, v237, 10, v238
	v_lshlrev_b32_e32 v238, 8, v232
	v_lshl_add_u32 v222, v235, 17, v238
	s_mov_b32 s45, 0xc0000
	v_mul_lo_u32 v237, v235, s45
	s_lshl_b32 s46, s57, 6
	s_sub_u32 s46, s46, 0x5000
	v_add_u32_e32 v238, s46, v238
	v_add_u32_e32 v223, v237, v238
	s_mov_b32 s45, 0x60000
	v_mul_lo_u32 v237, v235, s45
	v_lshlrev_b32_e32 v238, 10, v233
	v_lshl_add_u32 v238, v232, 7, v238
	s_lshl_b32 s46, s57, 5
	v_add_u32_e32 v238, s46, v238
	v_add_u32_e32 v227, v237, v238
	v_lshlrev_b32_e32 v228, 6, v235
	v_mov_b32_e32 v225, s65
	v_mov_b32_e32 v226, s66
	s_mov_b32 s99, 0
	v_readfirstlane_b32 s100, v0
	s_nop 1
	s_lshr_b32 s100, s100, 6
	s_nop 1
	v_readlane_b32 s41, v220, 0
	v_readlane_b32 s42, v220, 1
	v_readlane_b32 s43, v220, 2
.Lp4n_top_A:
	s_cmp_lt_u32 s99, 63
	s_cselect_b64 s[10:11], -1, 0
	s_mul_i32 s9, s52, 0x4400
	ds_read_b128 v[102:105], v193 offset:31232
	ds_read_b128 v[106:109], v192 offset:48640
	v_add_u32_e32 v159, s9, v190
	ds_read_b128 v[110:113], v192 offset:48704
	ds_read_b128 v[114:117], v193 offset:31296
	ds_read_b128 v[198:201], v159
	ds_read_b128 v[202:205], v159 offset:64
	s_waitcnt lgkmcnt(0)
	v_mfma_f32_16x16x32_bf16 v[102:105], v[102:105], v[106:109], 0
	s_mul_i32 s9, s52, 0x500
	s_add_i32 s87, s9, 0
	s_add_i32 s87, s87, 0x1d400
	s_waitcnt lgkmcnt(1)
	v_mfma_f32_16x16x32_bf16 v[106:109], v[198:201], v[106:109], 0
	v_mfma_f32_16x16x32_bf16 v[102:105], v[114:117], v[110:113], v[102:105]
	ds_read_b128 v[114:117], v193 offset:31360
	ds_read_b128 v[198:201], v192 offset:48768
	s_waitcnt lgkmcnt(2)
	v_mfma_f32_16x16x32_bf16 v[106:109], v[202:205], v[110:113], v[106:109]
	ds_read_b128 v[110:113], v193 offset:31424
	ds_read_b128 v[202:205], v192 offset:48832
	s_waitcnt lgkmcnt(2)
	v_mfma_f32_16x16x32_bf16 v[102:105], v[114:117], v[198:201], v[102:105]
	ds_read_b128 v[114:117], v159 offset:128
	ds_read_b128 v[206:209], v159 offset:192
	v_lshl_add_u32 v159, v189, 2, s87
	s_waitcnt lgkmcnt(2)
	v_mfma_f32_16x16x32_bf16 v[102:105], v[110:113], v[202:205], v[102:105]
	ds_read_b128 v[110:113], v159 offset:512
	s_waitcnt lgkmcnt(2)
	v_mfma_f32_16x16x32_bf16 v[106:109], v[114:117], v[198:201], v[106:109]
	s_nop 4
	v_sub_f32_e32 v105, v101, v105
	v_sub_f32_e32 v104, v100, v104
	v_sub_f32_e32 v103, v99, v103
	v_sub_f32_e32 v102, v98, v102
	v_cvt_pk_bf16_f32 v114, v102, v103
	s_waitcnt lgkmcnt(0)
	v_pk_mul_f32 v[102:103], v[102:103], v[110:111]
	v_cvt_pk_bf16_f32 v115, v104, v105
	v_pk_mul_f32 v[104:105], v[104:105], v[112:113]
	v_cvt_pk_bf16_f32 v102, v102, v103
	v_cvt_pk_bf16_f32 v103, v104, v105
	ds_write2st64_b64 v194, v[114:115], v[102:103] offset0:112 offset1:121
	ds_read_b128 v[110:113], v159
	v_mfma_f32_16x16x32_bf16 v[114:117], v[206:209], v[202:205], v[106:109]
.Lp4n_stg_A:
	s_cmp_lt_u32 s99, 63
	s_cbranch_scc0 .Lp4n_premid_A
	s_xor_b32 s14, s52, 1
	s_bfe_u32 s45, s42, 0x1000c
	s_cmp_eq_u32 s45, 0
	s_mul_i32 s8, s14, 0x4400
	s_cselect_b64 vcc, -1, 0
	v_add_u32_e32 v102, s8, v169
	v_cndmask_b32_e32 v106, v162, v161, vcc
	v_cndmask_b32_e32 v107, v164, v163, vcc
	v_cndmask_b32_e32 v108, v166, v165, vcc
	v_cndmask_b32_e32 v109, v168, v167, vcc
	s_mul_i32 s9, s14, 0x2400
	s_waitcnt vmcnt(11)
	ds_write_b128 v102, v[34:37]
	s_waitcnt vmcnt(10)
	ds_write_b128 v102, v[38:41] offset:8704
	ds_write_b128 v170, v[26:29]
	ds_write_b128 v170, v[30:33] offset:9216
	s_waitcnt vmcnt(9)
	v_and_b32_e32 v102, v42, v106
	v_and_b32_e32 v103, v43, v107
	v_and_b32_e32 v104, v44, v108
	v_and_b32_e32 v105, v45, v109
	ds_write_b128 v171, v[102:105] offset:17408
	s_waitcnt vmcnt(8)
	v_and_b32_e32 v102, v46, v106
	v_and_b32_e32 v103, v47, v107
	v_and_b32_e32 v104, v48, v108
	v_and_b32_e32 v105, v49, v109
	v_add_u32_e32 v106, s9, v172
	s_bfe_u32 s45, s42, 0x60016
	s_cmp_lg_u32 s45, 0
	ds_write_b128 v106, v[102:105]
	s_cbranch_scc1 .Lp4n_cwkeep_A
	s_waitcnt vmcnt(4)
	v_mov_b64_e32 v[84:85], v[24:25]
	v_mov_b64_e32 v[88:89], v[20:21]
	v_mov_b64_e32 v[92:93], v[16:17]
	v_mov_b64_e32 v[96:97], v[12:13]
	v_mov_b64_e32 v[82:83], v[22:23]
	v_mov_b64_e32 v[86:87], v[18:19]
	v_mov_b64_e32 v[90:91], v[14:15]
	v_mov_b64_e32 v[94:95], v[10:11]
.Lp4n_cwkeep_A:
	v_lshlrev_b32_e32 v102, 16, v128
	v_and_b32_e32 v103, 0xffff0000, v128
	v_pk_mul_f32 v[102:103], v[94:95], v[102:103]
	v_lshlrev_b32_e32 v104, 16, v129
	v_and_b32_e32 v105, 0xffff0000, v129
	v_pk_mul_f32 v[104:105], v[96:97], v[104:105]
	v_lshlrev_b32_e32 v106, 16, v130
	v_and_b32_e32 v107, 0xffff0000, v130
	v_pk_fma_f32 v[102:103], v[90:91], v[106:107], v[102:103]
	v_lshlrev_b32_e32 v108, 16, v131
	v_and_b32_e32 v109, 0xffff0000, v131
	v_pk_fma_f32 v[104:105], v[92:93], v[108:109], v[104:105]
	v_lshlrev_b32_e32 v106, 16, v132
	v_and_b32_e32 v107, 0xffff0000, v132
	v_pk_fma_f32 v[102:103], v[86:87], v[106:107], v[102:103]
	v_lshlrev_b32_e32 v108, 16, v133
	v_and_b32_e32 v109, 0xffff0000, v133
	v_pk_fma_f32 v[104:105], v[88:89], v[108:109], v[104:105]
	v_lshlrev_b32_e32 v106, 16, v136
	v_and_b32_e32 v107, 0xffff0000, v136
	v_pk_fma_f32 v[102:103], v[82:83], v[106:107], v[102:103]
	v_lshlrev_b32_e32 v108, 16, v137
	v_and_b32_e32 v109, 0xffff0000, v137
	v_pk_fma_f32 v[104:105], v[84:85], v[108:109], v[104:105]
	v_mul_f32_e32 v106, 0xbfb8aa3b, v102
	v_mul_f32_e32 v107, 0xbfb8aa3b, v103
	v_mul_f32_e32 v108, 0xbfb8aa3b, v104
	v_mul_f32_e32 v109, 0xbfb8aa3b, v105
	v_exp_f32_e32 v106, v106
	v_exp_f32_e32 v107, v107
	v_exp_f32_e32 v108, v108
	v_exp_f32_e32 v109, v109
	v_add_f32_e32 v106, 1.0, v106
	v_add_f32_e32 v107, 1.0, v107
	v_add_f32_e32 v108, 1.0, v108
	v_add_f32_e32 v109, 1.0, v109
	v_rcp_f32_e32 v106, v106
	v_rcp_f32_e32 v107, v107
	v_rcp_f32_e32 v108, v108
	v_rcp_f32_e32 v109, v109
	v_mul_f32_e32 v102, v102, v106
	v_mul_f32_e32 v103, v103, v107
	v_mul_f32_e32 v104, v104, v108
	v_mul_f32_e32 v105, v105, v109
	s_waitcnt vmcnt(7)
	v_mul_f32_e32 v102, v175, v102
	v_mul_f32_e32 v103, v175, v103
	v_mul_f32_e32 v104, v175, v104
	v_mul_f32_e32 v105, v175, v105
	v_cvt_pk_bf16_f32 v102, v102, s0
	v_cvt_pk_bf16_f32 v103, v103, s0
	v_cvt_pk_bf16_f32 v104, v104, s0
	v_cvt_pk_bf16_f32 v105, v105, s0
	v_add_u32_e32 v106, v173, v182
	ds_write_b16 v106, v102 offset:26624
	ds_write_b16 v106, v103 offset:26768
	ds_write_b16 v106, v104 offset:26912
	ds_write_b16 v106, v105 offset:27056
	s_and_saveexec_b64 s[8:9], s[4:5]
	s_cbranch_execz .Lp4n_w0done_A
	s_mulk_i32 s14, 0x500
	s_add_i32 s14, s14, 0
	s_add_i32 s14, s14, 0x1d400
	s_and_b64 s[20:21], vcc, exec
	s_cselect_b32 s20, 63, 0
	v_and_or_b32 v102, v195, 64, s20
	v_lshlrev_b32_e32 v102, 2, v102
	ds_bpermute_b32 v102, v102, v176
	v_mul_f32_e32 v103, 0x3fb8aa3b, v176
	v_exp_f32_e32 v103, v103
	v_lshl_add_u32 v105, v0, 2, s14
	s_waitcnt lgkmcnt(0)
	v_sub_f32_e32 v104, v102, v176
	v_mul_f32_e32 v104, 0x3fb8aa3b, v104
	v_exp_f32_e32 v104, v104
	v_mul_f32_e32 v106, v177, v103
	ds_write2st64_b32 v105, v103, v106 offset1:1
	ds_write_b32 v105, v104 offset:512
	s_and_b64 exec, exec, s[6:7]
	s_cbranch_execz .Lp4n_w0done_A
	v_mul_f32_e32 v102, 0x3fb8aa3b, v102
	v_exp_f32_e32 v102, v102
	v_mov_b32_e32 v103, s14
	ds_write_b32 v103, v102 offset:768

.Lp4n_premid_A:
.Lp4n_mid_A:
	s_waitcnt lgkmcnt(0)
	s_barrier
	v_mov_b32_e32 v102, s87
	ds_read_b32 v198, v102 offset:768
	ds_read_b128 v[102:105], v196 offset:61952
	ds_read_b128 v[106:109], v196 offset:64256
	s_mul_i32 s8, s52, 0x2400
	v_add_u32_e32 v159, s8, v191
	s_waitcnt lgkmcnt(2)
	v_pk_mul_f32 v[4:5], v[4:5], v[198:199] op_sel_hi:[1,0]
	v_pk_mul_f32 v[2:3], v[2:3], v[198:199] op_sel_hi:[1,0]
	v_pk_mul_f32 v[8:9], v[8:9], v[198:199] op_sel_hi:[1,0]
	v_pk_mul_f32 v[6:7], v[6:7], v[198:199] op_sel_hi:[1,0]
	s_waitcnt lgkmcnt(1)
	v_mfma_f32_16x16x32_bf16 v[2:5], v[74:77], v[102:105], v[2:5]
	ds_read_b128 v[102:105], v196 offset:62016
	s_waitcnt lgkmcnt(1)
	v_mfma_f32_16x16x32_bf16 v[6:9], v[74:77], v[106:109], v[6:9]
	v_readlane_b32 s8, v227, s99
	s_mov_b32 s9, 0
	s_waitcnt lgkmcnt(0)
	v_mfma_f32_16x16x32_bf16 v[102:105], v[78:81], v[102:105], v[2:5]
	s_nop 2
	ds_read_b128 v[2:5], v196 offset:64320
	ds_read_b128 v[198:201], v159
	ds_read_b128 v[202:205], v187 offset:57344
	s_waitcnt lgkmcnt(2)
	v_mfma_f32_16x16x32_bf16 v[106:109], v[78:81], v[2:5], v[6:9]
	v_mul_f32_e64 v4, v116, v112
	v_mul_f32_e64 v5, v117, v113
	v_pk_mul_f32 v[2:3], v[114:115], v[110:111]
	ds_read_b128 v[110:113], v159 offset:64
	ds_read_b128 v[6:9], v187 offset:57408
	s_waitcnt lgkmcnt(2)
	v_mfma_f32_16x16x32_bf16 v[2:5], v[198:201], v[202:205], v[2:5]
	s_bfe_u32 s45, s41, 0x10015
	s_cmp_eq_u32 s45, 0
	s_waitcnt lgkmcnt(0)
	v_mfma_f32_16x16x32_bf16 v[2:5], v[110:113], v[6:9], v[2:5]
	v_lshl_add_u64 v[6:7], s[8:9], 1, v[156:157]
	s_movk_i32 s8, 0x6000
	s_nop 5
	v_cvt_pk_bf16_f32 v2, v2, s0
	global_store_short v[6:7], v2, off
	v_add_co_u32_e32 v2, vcc, s50, v6
	v_cvt_pk_bf16_f32 v8, v3, s0
	s_nop 0
	v_addc_co_u32_e32 v3, vcc, 0, v7, vcc
	global_store_short v[2:3], v8, off
	v_add_co_u32_e32 v2, vcc, s8, v6
	v_cvt_pk_bf16_f32 v4, v4, s0
	s_nop 0
	v_addc_co_u32_e32 v3, vcc, 0, v7, vcc
	global_store_short v[2:3], v4, off
	v_add_co_u32_e32 v2, vcc, 0x9000, v6
	v_cvt_pk_bf16_f32 v4, v5, s0
	s_nop 0
	v_addc_co_u32_e32 v3, vcc, 0, v7, vcc
	global_store_short v[2:3], v4, off
	s_cbranch_scc1 .Lp4n_sjoin_A
	s_bfe_u32 s45, s41, 0x10014
	s_cmp_lg_u32 s45, 0
	s_cbranch_scc1 .Lp4n_nosst_A
	s_bfe_u32 s8, s41, 0x5000f
	s_lshl_b32 s8, s8, 4
	s_bfe_u32 s9, s41, 0x1000c
	s_lshl_b32 s9, s9, 3
	s_bfe_u32 s14, s41, 0x30009
	s_add_i32 s8, s14, s8
	s_bfe_u32 s14, s41, 0x2000d
	s_lshl_b32 s14, s14, 5
	s_add_i32 s8, s8, s9
	s_ashr_i32 s9, s8, 31
	s_lshl_b64 s[8:9], s[8:9], 16
	s_add_u32 s20, s72, s8
	s_addc_u32 s21, s73, s9
	s_lshl_b64 s[8:9], s[14:15], 2
	s_add_u32 s8, s20, s8
	s_addc_u32 s9, s21, s9
	v_lshl_add_u64 v[2:3], s[8:9], 0, v[126:127]
	v_lshl_add_u64 v[2:3], v[2:3], 0, s[18:19]
	v_lshl_add_u64 v[4:5], v[2:3], 0, v[144:145]
	v_lshl_add_u64 v[6:7], v[2:3], 0, v[146:147]
	v_lshl_add_u64 v[8:9], v[2:3], 0, v[148:149]
	v_lshl_add_u64 v[2:3], v[2:3], 0, v[150:151]
	global_store_dword v[4:5], v102, off
	global_store_dword v[6:7], v103, off
	global_store_dword v[8:9], v104, off
	global_store_dword v[2:3], v105, off
	global_store_dword v[4:5], v106, off offset:64
	global_store_dword v[6:7], v107, off offset:64
	global_store_dword v[8:9], v108, off offset:64
	global_store_dword v[2:3], v109, off offset:64

.Lp4n_top_B:
	s_cmp_lt_u32 s99, 63
	s_cselect_b64 s[10:11], -1, 0
	s_mul_i32 s9, s52, 0x4400
	ds_read_b128 v[2:5], v193 offset:31232
	ds_read_b128 v[6:9], v192 offset:48640
	v_add_u32_e32 v159, s9, v190
	ds_read_b128 v[110:113], v192 offset:48704
	ds_read_b128 v[114:117], v193 offset:31296
	ds_read_b128 v[198:201], v159
	ds_read_b128 v[202:205], v159 offset:64
	s_waitcnt lgkmcnt(0)
	v_mfma_f32_16x16x32_bf16 v[2:5], v[2:5], v[6:9], 0
	s_mul_i32 s9, s52, 0x500
	s_add_i32 s87, s9, 0
	s_add_i32 s87, s87, 0x1d400
	s_waitcnt lgkmcnt(1)
	v_mfma_f32_16x16x32_bf16 v[6:9], v[198:201], v[6:9], 0
	v_mfma_f32_16x16x32_bf16 v[2:5], v[114:117], v[110:113], v[2:5]
	ds_read_b128 v[114:117], v193 offset:31360
	ds_read_b128 v[198:201], v192 offset:48768
	s_waitcnt lgkmcnt(2)
	v_mfma_f32_16x16x32_bf16 v[6:9], v[202:205], v[110:113], v[6:9]
	ds_read_b128 v[110:113], v193 offset:31424
	ds_read_b128 v[202:205], v192 offset:48832
	s_waitcnt lgkmcnt(2)
	v_mfma_f32_16x16x32_bf16 v[2:5], v[114:117], v[198:201], v[2:5]
	ds_read_b128 v[114:117], v159 offset:128
	ds_read_b128 v[206:209], v159 offset:192
	v_lshl_add_u32 v159, v189, 2, s87
	s_waitcnt lgkmcnt(2)
	v_mfma_f32_16x16x32_bf16 v[2:5], v[110:113], v[202:205], v[2:5]
	ds_read_b128 v[110:113], v159 offset:512
	s_waitcnt lgkmcnt(2)
	v_mfma_f32_16x16x32_bf16 v[6:9], v[114:117], v[198:201], v[6:9]
	s_nop 4
	v_sub_f32_e32 v5, v101, v5
	v_sub_f32_e32 v4, v100, v4
	v_sub_f32_e32 v3, v99, v3
	v_sub_f32_e32 v2, v98, v2
	v_cvt_pk_bf16_f32 v114, v2, v3
	s_waitcnt lgkmcnt(0)
	v_pk_mul_f32 v[2:3], v[2:3], v[110:111]
	v_cvt_pk_bf16_f32 v115, v4, v5
	v_pk_mul_f32 v[4:5], v[4:5], v[112:113]
	v_cvt_pk_bf16_f32 v2, v2, v3
	v_cvt_pk_bf16_f32 v3, v4, v5
	ds_write2st64_b64 v194, v[114:115], v[2:3] offset0:112 offset1:121
	ds_read_b128 v[110:113], v159
	v_mfma_f32_16x16x32_bf16 v[114:117], v[206:209], v[202:205], v[6:9]
.Lp4n_stg_B:
	s_cmp_lt_u32 s99, 63
	s_cbranch_scc0 .Lp4n_premid_B
	s_xor_b32 s14, s52, 1
	s_bfe_u32 s45, s42, 0x1000c
	s_cmp_eq_u32 s45, 0
	s_mul_i32 s8, s14, 0x4400
	s_cselect_b64 vcc, -1, 0
	v_add_u32_e32 v2, s8, v169
	v_cndmask_b32_e32 v6, v162, v161, vcc
	v_cndmask_b32_e32 v7, v164, v163, vcc
	v_cndmask_b32_e32 v8, v166, v165, vcc
	v_cndmask_b32_e32 v9, v168, v167, vcc
	s_mul_i32 s9, s14, 0x2400
	s_waitcnt vmcnt(11)
	ds_write_b128 v2, v[58:61]
	s_waitcnt vmcnt(10)
	ds_write_b128 v2, v[62:65] offset:8704
	ds_write_b128 v170, v[50:53]
	ds_write_b128 v170, v[54:57] offset:9216
	s_waitcnt vmcnt(9)
	v_and_b32_e32 v2, v66, v6
	v_and_b32_e32 v3, v67, v7
	v_and_b32_e32 v4, v68, v8
	v_and_b32_e32 v5, v69, v9
	ds_write_b128 v171, v[2:5] offset:17408
	s_waitcnt vmcnt(8)
	v_and_b32_e32 v2, v70, v6
	v_and_b32_e32 v3, v71, v7
	v_and_b32_e32 v4, v72, v8
	v_and_b32_e32 v5, v73, v9
	v_add_u32_e32 v6, s9, v172
	s_bfe_u32 s45, s42, 0x60016
	s_cmp_lg_u32 s45, 0
	ds_write_b128 v6, v[2:5]
	s_cbranch_scc1 .Lp4n_cwkeep_B
	s_waitcnt vmcnt(4)
	v_mov_b64_e32 v[84:85], v[24:25]
	v_mov_b64_e32 v[88:89], v[20:21]
	v_mov_b64_e32 v[92:93], v[16:17]
	v_mov_b64_e32 v[96:97], v[12:13]
	v_mov_b64_e32 v[82:83], v[22:23]
	v_mov_b64_e32 v[86:87], v[18:19]
	v_mov_b64_e32 v[90:91], v[14:15]
	v_mov_b64_e32 v[94:95], v[10:11]
.Lp4n_cwkeep_B:
	v_lshlrev_b32_e32 v2, 16, v134
	v_and_b32_e32 v3, 0xffff0000, v134
	v_pk_mul_f32 v[2:3], v[94:95], v[2:3]
	v_lshlrev_b32_e32 v4, 16, v135
	v_and_b32_e32 v5, 0xffff0000, v135
	v_pk_mul_f32 v[4:5], v[96:97], v[4:5]
	v_lshlrev_b32_e32 v6, 16, v138
	v_and_b32_e32 v7, 0xffff0000, v138
	v_pk_fma_f32 v[2:3], v[90:91], v[6:7], v[2:3]
	v_lshlrev_b32_e32 v8, 16, v139
	v_and_b32_e32 v9, 0xffff0000, v139
	v_pk_fma_f32 v[4:5], v[92:93], v[8:9], v[4:5]
	v_lshlrev_b32_e32 v6, 16, v140
	v_and_b32_e32 v7, 0xffff0000, v140
	v_pk_fma_f32 v[2:3], v[86:87], v[6:7], v[2:3]
	v_lshlrev_b32_e32 v8, 16, v141
	v_and_b32_e32 v9, 0xffff0000, v141
	v_pk_fma_f32 v[4:5], v[88:89], v[8:9], v[4:5]
	v_lshlrev_b32_e32 v6, 16, v142
	v_and_b32_e32 v7, 0xffff0000, v142
	v_pk_fma_f32 v[2:3], v[82:83], v[6:7], v[2:3]
	v_lshlrev_b32_e32 v8, 16, v143
	v_and_b32_e32 v9, 0xffff0000, v143
	v_pk_fma_f32 v[4:5], v[84:85], v[8:9], v[4:5]
	v_mul_f32_e32 v6, 0xbfb8aa3b, v2
	v_mul_f32_e32 v7, 0xbfb8aa3b, v3
	v_mul_f32_e32 v8, 0xbfb8aa3b, v4
	v_mul_f32_e32 v9, 0xbfb8aa3b, v5
	v_exp_f32_e32 v6, v6
	v_exp_f32_e32 v7, v7
	v_exp_f32_e32 v8, v8
	v_exp_f32_e32 v9, v9
	v_add_f32_e32 v6, 1.0, v6
	v_add_f32_e32 v7, 1.0, v7
	v_add_f32_e32 v8, 1.0, v8
	v_add_f32_e32 v9, 1.0, v9
	v_rcp_f32_e32 v6, v6
	v_rcp_f32_e32 v7, v7
	v_rcp_f32_e32 v8, v8
	v_rcp_f32_e32 v9, v9
	v_mul_f32_e32 v2, v2, v6
	v_mul_f32_e32 v3, v3, v7
	v_mul_f32_e32 v4, v4, v8
	v_mul_f32_e32 v5, v5, v9
	s_waitcnt vmcnt(7)
	v_mul_f32_e32 v2, v181, v2
	v_mul_f32_e32 v3, v181, v3
	v_mul_f32_e32 v4, v181, v4
	v_mul_f32_e32 v5, v181, v5
	v_cvt_pk_bf16_f32 v2, v2, s0
	v_cvt_pk_bf16_f32 v3, v3, s0
	v_cvt_pk_bf16_f32 v4, v4, s0
	v_cvt_pk_bf16_f32 v5, v5, s0
	v_add_u32_e32 v6, v173, v182
	ds_write_b16 v6, v2 offset:26624
	ds_write_b16 v6, v3 offset:26768
	ds_write_b16 v6, v4 offset:26912
	ds_write_b16 v6, v5 offset:27056
	s_and_saveexec_b64 s[8:9], s[4:5]
	s_cbranch_execz .Lp4n_w0done_B
	s_mulk_i32 s14, 0x500
	s_add_i32 s14, s14, 0
	s_add_i32 s14, s14, 0x1d400
	s_and_b64 s[20:21], vcc, exec
	s_cselect_b32 s20, 63, 0
	v_and_or_b32 v2, v195, 64, s20
	v_lshlrev_b32_e32 v2, 2, v2
	ds_bpermute_b32 v2, v2, v184
	v_mul_f32_e32 v3, 0x3fb8aa3b, v184
	v_exp_f32_e32 v3, v3
	v_lshl_add_u32 v5, v0, 2, s14
	s_waitcnt lgkmcnt(0)
	v_sub_f32_e32 v4, v2, v184
	v_mul_f32_e32 v4, 0x3fb8aa3b, v4
	v_exp_f32_e32 v4, v4
	v_mul_f32_e32 v6, v185, v3
	ds_write2st64_b32 v5, v3, v6 offset1:1
	ds_write_b32 v5, v4 offset:512
	s_and_b64 exec, exec, s[6:7]
	s_cbranch_execz .Lp4n_w0done_B
	v_mul_f32_e32 v2, 0x3fb8aa3b, v2
	v_exp_f32_e32 v2, v2
	v_mov_b32_e32 v3, s14
	ds_write_b32 v3, v2 offset:768

.Lp4n_premid_B:
.Lp4n_mid_B:
	s_waitcnt lgkmcnt(0)
	s_barrier
	v_mov_b32_e32 v2, s87
	ds_read_b32 v198, v2 offset:768
	ds_read_b128 v[2:5], v196 offset:61952
	ds_read_b128 v[6:9], v196 offset:64256
	s_mul_i32 s8, s52, 0x2400
	v_add_u32_e32 v159, s8, v191
	s_waitcnt lgkmcnt(2)
	v_pk_mul_f32 v[104:105], v[104:105], v[198:199] op_sel_hi:[1,0]
	v_pk_mul_f32 v[102:103], v[102:103], v[198:199] op_sel_hi:[1,0]
	v_pk_mul_f32 v[108:109], v[108:109], v[198:199] op_sel_hi:[1,0]
	v_pk_mul_f32 v[106:107], v[106:107], v[198:199] op_sel_hi:[1,0]
	s_waitcnt lgkmcnt(1)
	v_mfma_f32_16x16x32_bf16 v[102:105], v[74:77], v[2:5], v[102:105]
	ds_read_b128 v[2:5], v196 offset:62016
	s_waitcnt lgkmcnt(1)
	v_mfma_f32_16x16x32_bf16 v[106:109], v[74:77], v[6:9], v[106:109]
	v_readlane_b32 s8, v227, s99
	s_mov_b32 s9, 0
	s_waitcnt lgkmcnt(0)
	v_mfma_f32_16x16x32_bf16 v[2:5], v[78:81], v[2:5], v[102:105]
	s_nop 2
	ds_read_b128 v[102:105], v196 offset:64320
	ds_read_b128 v[198:201], v159
	ds_read_b128 v[202:205], v187 offset:57344
	s_waitcnt lgkmcnt(2)
	v_mfma_f32_16x16x32_bf16 v[6:9], v[78:81], v[102:105], v[106:109]
	v_mul_f32_e64 v104, v116, v112
	v_mul_f32_e64 v105, v117, v113
	v_pk_mul_f32 v[102:103], v[114:115], v[110:111]
	ds_read_b128 v[110:113], v159 offset:64
	ds_read_b128 v[106:109], v187 offset:57408
	s_waitcnt lgkmcnt(2)
	v_mfma_f32_16x16x32_bf16 v[102:105], v[198:201], v[202:205], v[102:105]
	s_bfe_u32 s45, s41, 0x10015
	s_cmp_eq_u32 s45, 0
	s_waitcnt lgkmcnt(0)
	v_mfma_f32_16x16x32_bf16 v[102:105], v[110:113], v[106:109], v[102:105]
	v_lshl_add_u64 v[106:107], s[8:9], 1, v[156:157]
	s_movk_i32 s8, 0x6000
	s_nop 5
	v_cvt_pk_bf16_f32 v102, v102, s0
	global_store_short v[106:107], v102, off
	v_add_co_u32_e32 v102, vcc, s50, v106
	v_cvt_pk_bf16_f32 v108, v103, s0
	s_nop 0
	v_addc_co_u32_e32 v103, vcc, 0, v107, vcc
	global_store_short v[102:103], v108, off
	v_add_co_u32_e32 v102, vcc, s8, v106
	v_cvt_pk_bf16_f32 v104, v104, s0
	s_nop 0
	v_addc_co_u32_e32 v103, vcc, 0, v107, vcc
	global_store_short v[102:103], v104, off
	v_add_co_u32_e32 v102, vcc, 0x9000, v106
	v_cvt_pk_bf16_f32 v104, v105, s0
	s_nop 0
	v_addc_co_u32_e32 v103, vcc, 0, v107, vcc
	global_store_short v[102:103], v104, off
	s_cbranch_scc1 .Lp4n_sjoin_B
	s_bfe_u32 s45, s41, 0x10014
	s_cmp_lg_u32 s45, 0
	s_cbranch_scc1 .Lp4n_nosst_B
	s_bfe_u32 s8, s41, 0x5000f
	s_lshl_b32 s8, s8, 4
	s_bfe_u32 s9, s41, 0x1000c
	s_lshl_b32 s9, s9, 3
	s_bfe_u32 s14, s41, 0x30009
	s_add_i32 s8, s14, s8
	s_bfe_u32 s14, s41, 0x2000d
	s_lshl_b32 s14, s14, 5
	s_add_i32 s8, s8, s9
	s_ashr_i32 s9, s8, 31
	s_lshl_b64 s[8:9], s[8:9], 16
	s_add_u32 s20, s72, s8
	s_addc_u32 s21, s73, s9
	s_lshl_b64 s[8:9], s[14:15], 2
	s_add_u32 s8, s20, s8
	s_addc_u32 s9, s21, s9
	v_lshl_add_u64 v[102:103], s[8:9], 0, v[126:127]
	v_lshl_add_u64 v[102:103], v[102:103], 0, s[18:19]
	v_lshl_add_u64 v[104:105], v[102:103], 0, v[144:145]
	v_lshl_add_u64 v[106:107], v[102:103], 0, v[146:147]
	v_lshl_add_u64 v[108:109], v[102:103], 0, v[148:149]
	v_lshl_add_u64 v[102:103], v[102:103], 0, v[150:151]
	global_store_dword v[104:105], v2, off
	global_store_dword v[106:107], v3, off
	global_store_dword v[108:109], v4, off
	global_store_dword v[102:103], v5, off
	global_store_dword v[104:105], v6, off offset:64
	global_store_dword v[106:107], v7, off offset:64
	global_store_dword v[108:109], v8, off offset:64
	global_store_dword v[102:103], v9, off offset:64

.LBB0_1004:
	v_lshl_add_u64 v[4:5], s[14:15], 0, v[36:37]
	v_lshl_add_u64 v[6:7], s[10:11], 0, v[36:37]
	global_load_dword v14, v[4:5], off
	v_add_co_u32_e32 v4, vcc, 0x6000, v6
	v_lshl_add_u64 v[8:9], s[16:17], 0, v[36:37]
	s_nop 0
	v_addc_co_u32_e32 v5, vcc, 0, v7, vcc
	v_add_co_u32_e32 v10, vcc, 0xf000, v6
	s_add_u32 s16, s16, 0x800
	s_nop 0
	v_addc_co_u32_e32 v11, vcc, 0, v7, vcc
	v_add_co_u32_e32 v12, vcc, 0x18000, v6
	global_load_dword v15, v[4:5], off
	global_load_dword v16, v[10:11], off
	v_addc_co_u32_e32 v13, vcc, 0, v7, vcc
	v_add_co_u32_e32 v4, vcc, 0x21000, v6
	s_addc_u32 s17, s17, 0
	s_nop 0
	v_addc_co_u32_e32 v5, vcc, 0, v7, vcc
	v_add_co_u32_e32 v10, vcc, 0x2a000, v6
	global_load_dword v17, v[12:13], off
	global_load_dword v18, v[4:5], off
	v_addc_co_u32_e32 v11, vcc, 0, v7, vcc
	v_add_co_u32_e32 v4, vcc, 0x33000, v6
	s_nop 1
	v_addc_co_u32_e32 v5, vcc, 0, v7, vcc
	v_add_co_u32_e32 v12, vcc, 0x3c000, v6
	global_load_dword v19, v[10:11], off
	global_load_dword v20, v[4:5], off
	v_addc_co_u32_e32 v13, vcc, 0, v7, vcc
	v_add_co_u32_e32 v4, vcc, 0x45000, v6
	s_nop 1
	v_addc_co_u32_e32 v5, vcc, 0, v7, vcc
	v_add_co_u32_e32 v10, vcc, 0x4e000, v6
	global_load_dword v21, v[12:13], off
	global_load_dword v22, v[4:5], off
	v_addc_co_u32_e32 v11, vcc, 0, v7, vcc
	v_add_co_u32_e32 v4, vcc, 0x57000, v6
	s_nop 1
	v_addc_co_u32_e32 v5, vcc, 0, v7, vcc
	v_add_co_u32_e32 v12, vcc, 0x60000, v6
	global_load_dword v23, v[10:11], off
	global_load_dword v24, v[4:5], off
	v_addc_co_u32_e32 v13, vcc, 0, v7, vcc
	v_add_co_u32_e32 v4, vcc, 0x69000, v6
	s_nop 1
	v_addc_co_u32_e32 v5, vcc, 0, v7, vcc
	v_add_co_u32_e32 v10, vcc, 0x72000, v6
	global_load_dword v25, v[12:13], off
	global_load_dword v26, v[4:5], off
	v_addc_co_u32_e32 v11, vcc, 0, v7, vcc
	v_add_co_u32_e32 v4, vcc, 0x7b000, v6
	s_nop 1
	v_addc_co_u32_e32 v5, vcc, 0, v7, vcc
	v_add_co_u32_e32 v12, vcc, 0x84000, v6
	global_load_dword v27, v[10:11], off
	global_load_dword v28, v[4:5], off
	v_addc_co_u32_e32 v13, vcc, 0, v7, vcc
	v_add_co_u32_e32 v4, vcc, 0x8d000, v6
	s_nop 1
	v_addc_co_u32_e32 v5, vcc, 0, v7, vcc
	global_load_dword v6, v[12:13], off
	global_load_dword v7, v[4:5], off
	global_load_dword v10, v[8:9], off
	v_add_co_u32_e32 v3, vcc, 0x200, v3
	s_xor_b64 s[18:19], vcc, -1
	s_add_u32 s10, s10, 0x800
	s_addc_u32 s11, s11, 0
	s_add_u32 s14, s14, 0x800
	s_addc_u32 s15, s15, 0
	s_and_b64 s[18:19], exec, s[18:19]
	s_or_b64 s[12:13], s[18:19], s[12:13]
	s_waitcnt vmcnt(16)
	v_add_f32_e32 v4, v14, v15
	s_waitcnt vmcnt(15)
	v_add_f32_e32 v4, v4, v16
	s_waitcnt vmcnt(14)
	v_add_f32_e32 v4, v4, v17
	s_waitcnt vmcnt(13)
	v_add_f32_e32 v4, v4, v18
	s_waitcnt vmcnt(12)
	v_add_f32_e32 v4, v4, v19
	s_waitcnt vmcnt(11)
	v_add_f32_e32 v4, v4, v20
	s_waitcnt vmcnt(10)
	v_add_f32_e32 v4, v4, v21
	s_waitcnt vmcnt(9)
	v_add_f32_e32 v4, v4, v22
	s_waitcnt vmcnt(8)
	v_add_f32_e32 v4, v4, v23
	s_waitcnt vmcnt(7)
	v_add_f32_e32 v4, v4, v24
	s_waitcnt vmcnt(6)
	v_add_f32_e32 v4, v4, v25
	s_waitcnt vmcnt(5)
	v_add_f32_e32 v4, v4, v26
	s_waitcnt vmcnt(4)
	v_add_f32_e32 v4, v4, v27
	s_waitcnt vmcnt(3)
	v_add_f32_e32 v4, v4, v28
	s_waitcnt vmcnt(2)
	v_add_f32_e32 v4, v4, v6
	s_waitcnt vmcnt(1)
	v_add_f32_e32 v4, v4, v7
	s_waitcnt vmcnt(0)
	v_mul_f32_e32 v4, v4, v10
	ds_write_b32 v2, v4
	v_add_u32_e32 v2, 0x800, v2
	s_andn2_b64 exec, exec, s[12:13]
	s_cbranch_execnz .LBB0_1004
	s_or_b64 exec, exec, s[12:13]
	s_waitcnt lgkmcnt(0)
	s_barrier
	ds_read_b128 v[2:5], v1
	ds_read_b128 v[6:9], v1 offset:1024
	ds_read_b128 v[10:13], v1 offset:2048
	ds_read_b128 v[14:17], v1 offset:3072
	v_lshlrev_b32_e32 v79, 2, v34
	v_lshlrev_b32_e32 v80, 1, v34
	s_cmpk_lt_u32 s27, 0x80
	s_cselect_b32 s28, 0, 1
	s_cmp_eq_u32 s28, 0
	s_cbranch_scc1 .Lp7n_norow
	s_lshl_b32 s2, s21, 4
	s_and_b32 s2, s2, 0xfc00
	s_add_u32 s10, s74, 0x94000
	s_addc_u32 s11, s75, 0
	s_add_u32 s10, s10, s2
	s_addc_u32 s11, s11, 0
	global_load_dwordx4 v[62:65], v79, s[10:11]
	s_add_u32 s10, s10, 0x10000
	s_addc_u32 s11, s11, 0
	global_load_dwordx4 v[66:69], v79, s[10:11]
.Lp7n_norow:
	s_waitcnt lgkmcnt(0)
	s_add_u32 s2, s21, 0
	s_mul_i32 s12, s2, 0x3000
	s_add_u32 s10, s74, 0x39c4000
	s_addc_u32 s11, s75, 0
	s_add_u32 s10, s10, s12
	s_addc_u32 s11, s11, 0
	global_load_dwordx2 v[148:149], v80, s[10:11] offset:0 nt
	global_load_dwordx2 v[150:151], v80, s[10:11] offset:512 nt
	global_load_dwordx2 v[152:153], v80, s[10:11] offset:1024 nt
	global_load_dwordx2 v[154:155], v80, s[10:11] offset:1536 nt
	s_cmpk_lt_u32 s2, 0x2000
	s_cselect_b32 s10, s4, s6
	s_cselect_b32 s11, s5, s7
	s_and_b32 s12, s2, 0x1fff
	s_lshl_b32 s12, s12, 12
	s_add_u32 s10, s10, s12
	s_addc_u32 s11, s11, 0
	global_load_dwordx4 v[84:87], v79, s[10:11] offset:0 nt
	global_load_dwordx4 v[88:91], v79, s[10:11] offset:1024 nt
	global_load_dwordx4 v[92:95], v79, s[10:11] offset:2048 nt
	global_load_dwordx4 v[96:99], v79, s[10:11] offset:3072 nt
	s_cmp_eq_u32 s28, 0
	s_cbranch_scc1 .Lp7n_nocol_0
	s_and_b32 s12, s2, 63
	s_lshl_b32 s12, s12, 10
	s_add_u32 s10, s74, 0x94000
	s_addc_u32 s11, s75, 0
	s_add_u32 s10, s10, s12
	s_addc_u32 s11, s11, 0
	global_load_dwordx4 v[18:21], v79, s[10:11]
	s_add_u32 s10, s10, 0x10000
	s_addc_u32 s11, s11, 0
	global_load_dwordx4 v[22:25], v79, s[10:11]
.Lp7n_nocol_0:
	s_add_u32 s2, s21, 1
	s_mul_i32 s12, s2, 0x3000
	s_add_u32 s10, s74, 0x39c4000
	s_addc_u32 s11, s75, 0
	s_add_u32 s10, s10, s12
	s_addc_u32 s11, s11, 0
	global_load_dwordx2 v[156:157], v80, s[10:11] offset:0 nt
	global_load_dwordx2 v[158:159], v80, s[10:11] offset:512 nt
	global_load_dwordx2 v[160:161], v80, s[10:11] offset:1024 nt
	global_load_dwordx2 v[162:163], v80, s[10:11] offset:1536 nt
	s_cmpk_lt_u32 s2, 0x2000
	s_cselect_b32 s10, s4, s6
	s_cselect_b32 s11, s5, s7
	s_and_b32 s12, s2, 0x1fff
	s_lshl_b32 s12, s12, 12
	s_add_u32 s10, s10, s12
	s_addc_u32 s11, s11, 0
	global_load_dwordx4 v[100:103], v79, s[10:11] offset:0 nt
	global_load_dwordx4 v[104:107], v79, s[10:11] offset:1024 nt
	global_load_dwordx4 v[108:111], v79, s[10:11] offset:2048 nt
	global_load_dwordx4 v[112:115], v79, s[10:11] offset:3072 nt
	s_cmp_eq_u32 s28, 0
	s_cbranch_scc1 .Lp7n_nocol_1
	s_and_b32 s12, s2, 63
	s_lshl_b32 s12, s12, 10
	s_add_u32 s10, s74, 0x94000
	s_addc_u32 s11, s75, 0
	s_add_u32 s10, s10, s12
	s_addc_u32 s11, s11, 0
	global_load_dwordx4 v[26:29], v79, s[10:11]
	s_add_u32 s10, s10, 0x10000
	s_addc_u32 s11, s11, 0
	global_load_dwordx4 v[30:33], v79, s[10:11]
.Lp7n_nocol_1:
	s_add_u32 s2, s21, 2
	s_mul_i32 s12, s2, 0x3000
	s_add_u32 s10, s74, 0x39c4000
	s_addc_u32 s11, s75, 0
	s_add_u32 s10, s10, s12
	s_addc_u32 s11, s11, 0
	global_load_dwordx2 v[164:165], v80, s[10:11] offset:0 nt
	global_load_dwordx2 v[166:167], v80, s[10:11] offset:512 nt
	global_load_dwordx2 v[168:169], v80, s[10:11] offset:1024 nt
	global_load_dwordx2 v[170:171], v80, s[10:11] offset:1536 nt
	s_cmpk_lt_u32 s2, 0x2000
	s_cselect_b32 s10, s4, s6
	s_cselect_b32 s11, s5, s7
	s_and_b32 s12, s2, 0x1fff
	s_lshl_b32 s12, s12, 12
	s_add_u32 s10, s10, s12
	s_addc_u32 s11, s11, 0
	global_load_dwordx4 v[116:119], v79, s[10:11] offset:0 nt
	global_load_dwordx4 v[120:123], v79, s[10:11] offset:1024 nt
	global_load_dwordx4 v[124:127], v79, s[10:11] offset:2048 nt
	global_load_dwordx4 v[128:131], v79, s[10:11] offset:3072 nt
	s_cmp_eq_u32 s28, 0
	s_cbranch_scc1 .Lp7n_nocol_2
	s_and_b32 s12, s2, 63
	s_lshl_b32 s12, s12, 10
	s_add_u32 s10, s74, 0x94000
	s_addc_u32 s11, s75, 0
	s_add_u32 s10, s10, s12
	s_addc_u32 s11, s11, 0
	global_load_dwordx4 v[46:49], v79, s[10:11]
	s_add_u32 s10, s10, 0x10000
	s_addc_u32 s11, s11, 0
	global_load_dwordx4 v[50:53], v79, s[10:11]
.Lp7n_nocol_2:
	s_add_u32 s2, s21, 3
	s_mul_i32 s12, s2, 0x3000
	s_add_u32 s10, s74, 0x39c4000
	s_addc_u32 s11, s75, 0
	s_add_u32 s10, s10, s12
	s_addc_u32 s11, s11, 0
	global_load_dwordx2 v[172:173], v80, s[10:11] offset:0 nt
	global_load_dwordx2 v[174:175], v80, s[10:11] offset:512 nt
	global_load_dwordx2 v[176:177], v80, s[10:11] offset:1024 nt
	global_load_dwordx2 v[178:179], v80, s[10:11] offset:1536 nt
	s_cmpk_lt_u32 s2, 0x2000
	s_cselect_b32 s10, s4, s6
	s_cselect_b32 s11, s5, s7
	s_and_b32 s12, s2, 0x1fff
	s_lshl_b32 s12, s12, 12
	s_add_u32 s10, s10, s12
	s_addc_u32 s11, s11, 0
	global_load_dwordx4 v[132:135], v79, s[10:11] offset:0 nt
	global_load_dwordx4 v[136:139], v79, s[10:11] offset:1024 nt
	global_load_dwordx4 v[140:143], v79, s[10:11] offset:2048 nt
	global_load_dwordx4 v[144:147], v79, s[10:11] offset:3072 nt
	s_cmp_eq_u32 s28, 0
	s_cbranch_scc1 .Lp7n_nocol_3
	s_and_b32 s12, s2, 63
	s_lshl_b32 s12, s12, 10
	s_add_u32 s10, s74, 0x94000
	s_addc_u32 s11, s75, 0
	s_add_u32 s10, s10, s12
	s_addc_u32 s11, s11, 0
	global_load_dwordx4 v[54:57], v79, s[10:11]
	s_add_u32 s10, s10, 0x10000
	s_addc_u32 s11, s11, 0
	global_load_dwordx4 v[58:61], v79, s[10:11]
.Lp7n_nocol_3:
	s_waitcnt vmcnt(0)
	s_cmp_eq_u32 s28, 0
	s_cbranch_scc1 .Lp7n_nope_0
	v_pk_add_f32 v[84:85], v[84:85], v[62:63]
	v_pk_add_f32 v[86:87], v[86:87], v[64:65]
	v_pk_add_f32 v[88:89], v[88:89], v[66:67]
	v_pk_add_f32 v[90:91], v[90:91], v[68:69]
	v_pk_add_f32 v[92:93], v[92:93], v[18:19]
	v_pk_add_f32 v[94:95], v[94:95], v[20:21]
	v_pk_add_f32 v[96:97], v[96:97], v[22:23]
	v_pk_add_f32 v[98:99], v[98:99], v[24:25]
	v_pk_add_f32 v[100:101], v[100:101], v[62:63]
	v_pk_add_f32 v[102:103], v[102:103], v[64:65]
	v_pk_add_f32 v[104:105], v[104:105], v[66:67]
	v_pk_add_f32 v[106:107], v[106:107], v[68:69]
	v_pk_add_f32 v[108:109], v[108:109], v[26:27]
	v_pk_add_f32 v[110:111], v[110:111], v[28:29]
	v_pk_add_f32 v[112:113], v[112:113], v[30:31]
	v_pk_add_f32 v[114:115], v[114:115], v[32:33]
	v_pk_add_f32 v[116:117], v[116:117], v[62:63]
	v_pk_add_f32 v[118:119], v[118:119], v[64:65]
	v_pk_add_f32 v[120:121], v[120:121], v[66:67]
	v_pk_add_f32 v[122:123], v[122:123], v[68:69]
	v_pk_add_f32 v[124:125], v[124:125], v[46:47]
	v_pk_add_f32 v[126:127], v[126:127], v[48:49]
	v_pk_add_f32 v[128:129], v[128:129], v[50:51]
	v_pk_add_f32 v[130:131], v[130:131], v[52:53]
	v_pk_add_f32 v[132:133], v[132:133], v[62:63]
	v_pk_add_f32 v[134:135], v[134:135], v[64:65]
	v_pk_add_f32 v[136:137], v[136:137], v[66:67]
	v_pk_add_f32 v[138:139], v[138:139], v[68:69]
	v_pk_add_f32 v[140:141], v[140:141], v[54:55]
	v_pk_add_f32 v[142:143], v[142:143], v[56:57]
	v_pk_add_f32 v[144:145], v[144:145], v[58:59]
	v_pk_add_f32 v[146:147], v[146:147], v[60:61]
.Lp7n_nope_0:
	v_lshlrev_b32_e32 v180, 16, v148
	v_and_b32_e32 v181, 0xffff0000, v148
	v_lshlrev_b32_e32 v182, 16, v149
	v_and_b32_e32 v183, 0xffff0000, v149
	v_lshlrev_b32_e32 v184, 16, v150
	v_and_b32_e32 v185, 0xffff0000, v150
	v_lshlrev_b32_e32 v186, 16, v151
	v_and_b32_e32 v187, 0xffff0000, v151
	v_lshlrev_b32_e32 v188, 16, v152
	v_and_b32_e32 v189, 0xffff0000, v152
	v_lshlrev_b32_e32 v190, 16, v153
	v_and_b32_e32 v191, 0xffff0000, v153
	v_lshlrev_b32_e32 v192, 16, v154
	v_and_b32_e32 v193, 0xffff0000, v154
	v_lshlrev_b32_e32 v194, 16, v155
	v_and_b32_e32 v195, 0xffff0000, v155
	v_lshlrev_b32_e32 v196, 16, v156
	v_and_b32_e32 v197, 0xffff0000, v156
	v_lshlrev_b32_e32 v198, 16, v157
	v_and_b32_e32 v199, 0xffff0000, v157
	v_lshlrev_b32_e32 v200, 16, v158
	v_and_b32_e32 v201, 0xffff0000, v158
	v_lshlrev_b32_e32 v202, 16, v159
	v_and_b32_e32 v203, 0xffff0000, v159
	v_lshlrev_b32_e32 v204, 16, v160
	v_and_b32_e32 v205, 0xffff0000, v160
	v_lshlrev_b32_e32 v206, 16, v161
	v_and_b32_e32 v207, 0xffff0000, v161
	v_lshlrev_b32_e32 v208, 16, v162
	v_and_b32_e32 v209, 0xffff0000, v162
	v_lshlrev_b32_e32 v210, 16, v163
	v_and_b32_e32 v211, 0xffff0000, v163
	v_lshlrev_b32_e32 v212, 16, v164
	v_and_b32_e32 v213, 0xffff0000, v164
	v_lshlrev_b32_e32 v214, 16, v165
	v_and_b32_e32 v215, 0xffff0000, v165
	v_lshlrev_b32_e32 v216, 16, v166
	v_and_b32_e32 v217, 0xffff0000, v166
	v_lshlrev_b32_e32 v218, 16, v167
	v_and_b32_e32 v219, 0xffff0000, v167
	v_lshlrev_b32_e32 v220, 16, v168
	v_and_b32_e32 v221, 0xffff0000, v168
	v_lshlrev_b32_e32 v222, 16, v169
	v_and_b32_e32 v223, 0xffff0000, v169
	v_lshlrev_b32_e32 v224, 16, v170
	v_and_b32_e32 v225, 0xffff0000, v170
	v_lshlrev_b32_e32 v226, 16, v171
	v_and_b32_e32 v227, 0xffff0000, v171
	v_lshlrev_b32_e32 v228, 16, v172
	v_and_b32_e32 v229, 0xffff0000, v172
	v_lshlrev_b32_e32 v230, 16, v173
	v_and_b32_e32 v231, 0xffff0000, v173
	v_lshlrev_b32_e32 v232, 16, v174
	v_and_b32_e32 v233, 0xffff0000, v174
	v_lshlrev_b32_e32 v234, 16, v175
	v_and_b32_e32 v235, 0xffff0000, v175
	v_lshlrev_b32_e32 v236, 16, v176
	v_and_b32_e32 v237, 0xffff0000, v176
	v_lshlrev_b32_e32 v238, 16, v177
	v_and_b32_e32 v239, 0xffff0000, v177
	v_lshlrev_b32_e32 v240, 16, v178
	v_and_b32_e32 v241, 0xffff0000, v178
	v_lshlrev_b32_e32 v242, 16, v179
	v_and_b32_e32 v243, 0xffff0000, v179
	v_pk_mul_f32 v[148:149], v[180:181], v[180:181]
	v_pk_mul_f32 v[156:157], v[196:197], v[196:197]
	v_pk_mul_f32 v[164:165], v[212:213], v[212:213]
	v_pk_mul_f32 v[172:173], v[228:229], v[228:229]
	v_pk_fma_f32 v[148:149], v[182:183], v[182:183], v[148:149]
	v_pk_fma_f32 v[156:157], v[198:199], v[198:199], v[156:157]
	v_pk_fma_f32 v[164:165], v[214:215], v[214:215], v[164:165]
	v_pk_fma_f32 v[172:173], v[230:231], v[230:231], v[172:173]
	v_pk_fma_f32 v[148:149], v[184:185], v[184:185], v[148:149]
	v_pk_fma_f32 v[156:157], v[200:201], v[200:201], v[156:157]
	v_pk_fma_f32 v[164:165], v[216:217], v[216:217], v[164:165]
	v_pk_fma_f32 v[172:173], v[232:233], v[232:233], v[172:173]
	v_pk_fma_f32 v[148:149], v[186:187], v[186:187], v[148:149]
	v_pk_fma_f32 v[156:157], v[202:203], v[202:203], v[156:157]
	v_pk_fma_f32 v[164:165], v[218:219], v[218:219], v[164:165]
	v_pk_fma_f32 v[172:173], v[234:235], v[234:235], v[172:173]
	v_pk_fma_f32 v[148:149], v[188:189], v[188:189], v[148:149]
	v_pk_fma_f32 v[156:157], v[204:205], v[204:205], v[156:157]
	v_pk_fma_f32 v[164:165], v[220:221], v[220:221], v[164:165]
	v_pk_fma_f32 v[172:173], v[236:237], v[236:237], v[172:173]
	v_pk_fma_f32 v[148:149], v[190:191], v[190:191], v[148:149]
	v_pk_fma_f32 v[156:157], v[206:207], v[206:207], v[156:157]
	v_pk_fma_f32 v[164:165], v[222:223], v[222:223], v[164:165]
	v_pk_fma_f32 v[172:173], v[238:239], v[238:239], v[172:173]
	v_pk_fma_f32 v[148:149], v[192:193], v[192:193], v[148:149]
	v_pk_fma_f32 v[156:157], v[208:209], v[208:209], v[156:157]
	v_pk_fma_f32 v[164:165], v[224:225], v[224:225], v[164:165]
	v_pk_fma_f32 v[172:173], v[240:241], v[240:241], v[172:173]
	v_pk_fma_f32 v[148:149], v[194:195], v[194:195], v[148:149]
	v_pk_fma_f32 v[156:157], v[210:211], v[210:211], v[156:157]
	v_pk_fma_f32 v[164:165], v[226:227], v[226:227], v[164:165]
	v_pk_fma_f32 v[172:173], v[242:243], v[242:243], v[172:173]
	v_add_f32_e32 v148, v148, v149
	v_add_f32_e32 v156, v156, v157
	v_add_f32_e32 v164, v164, v165
	v_add_f32_e32 v172, v172, v173
	ds_bpermute_b32 v149, v35, v148
	ds_bpermute_b32 v157, v35, v156
	ds_bpermute_b32 v165, v35, v164
	ds_bpermute_b32 v173, v35, v172
	s_waitcnt lgkmcnt(0)
	v_add_f32_e32 v148, v148, v149
	v_add_f32_e32 v156, v156, v157
	v_add_f32_e32 v164, v164, v165
	v_add_f32_e32 v172, v172, v173
	ds_bpermute_b32 v149, v70, v148
	ds_bpermute_b32 v157, v70, v156
	ds_bpermute_b32 v165, v70, v164
	ds_bpermute_b32 v173, v70, v172
	s_waitcnt lgkmcnt(0)
	v_add_f32_e32 v148, v148, v149
	v_add_f32_e32 v156, v156, v157
	v_add_f32_e32 v164, v164, v165
	v_add_f32_e32 v172, v172, v173
	ds_bpermute_b32 v149, v71, v148
	ds_bpermute_b32 v157, v71, v156
	ds_bpermute_b32 v165, v71, v164
	ds_bpermute_b32 v173, v71, v172
	s_waitcnt lgkmcnt(0)
	v_add_f32_e32 v148, v148, v149
	v_add_f32_e32 v156, v156, v157
	v_add_f32_e32 v164, v164, v165
	v_add_f32_e32 v172, v172, v173
	ds_bpermute_b32 v149, v72, v148
	ds_bpermute_b32 v157, v72, v156
	ds_bpermute_b32 v165, v72, v164
	ds_bpermute_b32 v173, v72, v172
	s_waitcnt lgkmcnt(0)
	v_add_f32_e32 v148, v148, v149
	v_add_f32_e32 v156, v156, v157
	v_add_f32_e32 v164, v164, v165
	v_add_f32_e32 v172, v172, v173
	ds_bpermute_b32 v149, v73, v148
	ds_bpermute_b32 v157, v73, v156
	ds_bpermute_b32 v165, v73, v164
	ds_bpermute_b32 v173, v73, v172
	s_waitcnt lgkmcnt(0)
	v_add_f32_e32 v148, v148, v149
	v_add_f32_e32 v156, v156, v157
	v_add_f32_e32 v164, v164, v165
	v_add_f32_e32 v172, v172, v173
	ds_bpermute_b32 v149, v74, v148
	ds_bpermute_b32 v157, v74, v156
	ds_bpermute_b32 v165, v74, v164
	ds_bpermute_b32 v173, v74, v172
	s_waitcnt lgkmcnt(0)
	v_add_f32_e32 v148, v148, v149
	v_add_f32_e32 v156, v156, v157
	v_add_f32_e32 v164, v164, v165
	v_add_f32_e32 v172, v172, v173
	v_fmamk_f32 v148, v148, 0x3a800000, v77
	v_fmamk_f32 v156, v156, 0x3a800000, v77
	v_fmamk_f32 v164, v164, 0x3a800000, v77
	v_fmamk_f32 v172, v172, 0x3a800000, v77
	v_mul_f32_e32 v150, 0x4b800000, v148
	v_cmp_gt_f32_e32 vcc, s26, v148
	s_nop 1
	v_cndmask_b32_e32 v148, v148, v150, vcc
	v_rsq_f32_e32 v148, v148
	s_nop 0
	v_mul_f32_e32 v150, 0x45800000, v148
	v_cndmask_b32_e32 v148, v148, v150, vcc
	v_mul_f32_e32 v158, 0x4b800000, v156
	v_cmp_gt_f32_e32 vcc, s26, v156
	s_nop 1
	v_cndmask_b32_e32 v156, v156, v158, vcc
	v_rsq_f32_e32 v156, v156
	s_nop 0
	v_mul_f32_e32 v158, 0x45800000, v156
	v_cndmask_b32_e32 v156, v156, v158, vcc
	v_mul_f32_e32 v166, 0x4b800000, v164
	v_cmp_gt_f32_e32 vcc, s26, v164
	s_nop 1
	v_cndmask_b32_e32 v164, v164, v166, vcc
	v_rsq_f32_e32 v164, v164
	s_nop 0
	v_mul_f32_e32 v166, 0x45800000, v164
	v_cndmask_b32_e32 v164, v164, v166, vcc
	v_mul_f32_e32 v174, 0x4b800000, v172
	v_cmp_gt_f32_e32 vcc, s26, v172
	s_nop 1
	v_cndmask_b32_e32 v172, v172, v174, vcc
	v_rsq_f32_e32 v172, v172
	s_nop 0
	v_mul_f32_e32 v174, 0x45800000, v172
	v_cndmask_b32_e32 v172, v172, v174, vcc
	s_add_u32 s2, s21, 0
	s_lshl_b32 s2, s2, 12
	s_add_u32 s10, s72, s2
	s_addc_u32 s11, s73, 0
	v_pk_mul_f32 v[180:181], v[180:181], v[148:149] op_sel_hi:[1,0]
	v_pk_mul_f32 v[182:183], v[182:183], v[148:149] op_sel_hi:[1,0]
	v_pk_fma_f32 v[84:85], v[2:3], v[180:181], v[84:85]
	v_pk_fma_f32 v[86:87], v[4:5], v[182:183], v[86:87]
	global_store_dwordx4 v79, v[84:87], s[10:11] offset:0 nt
	v_pk_mul_f32 v[184:185], v[184:185], v[148:149] op_sel_hi:[1,0]
	v_pk_mul_f32 v[186:187], v[186:187], v[148:149] op_sel_hi:[1,0]
	v_pk_fma_f32 v[88:89], v[6:7], v[184:185], v[88:89]
	v_pk_fma_f32 v[90:91], v[8:9], v[186:187], v[90:91]
	global_store_dwordx4 v79, v[88:91], s[10:11] offset:1024 nt
	v_pk_mul_f32 v[188:189], v[188:189], v[148:149] op_sel_hi:[1,0]
	v_pk_mul_f32 v[190:191], v[190:191], v[148:149] op_sel_hi:[1,0]
	v_pk_fma_f32 v[92:93], v[10:11], v[188:189], v[92:93]
	v_pk_fma_f32 v[94:95], v[12:13], v[190:191], v[94:95]
	global_store_dwordx4 v79, v[92:95], s[10:11] offset:2048 nt
	v_pk_mul_f32 v[192:193], v[192:193], v[148:149] op_sel_hi:[1,0]
	v_pk_mul_f32 v[194:195], v[194:195], v[148:149] op_sel_hi:[1,0]
	v_pk_fma_f32 v[96:97], v[14:15], v[192:193], v[96:97]
	v_pk_fma_f32 v[98:99], v[16:17], v[194:195], v[98:99]
	global_store_dwordx4 v79, v[96:99], s[10:11] offset:3072 nt
	s_add_u32 s2, s21, 1
	s_lshl_b32 s2, s2, 12
	s_add_u32 s10, s72, s2
	s_addc_u32 s11, s73, 0
	v_pk_mul_f32 v[196:197], v[196:197], v[156:157] op_sel_hi:[1,0]
	v_pk_mul_f32 v[198:199], v[198:199], v[156:157] op_sel_hi:[1,0]
	v_pk_fma_f32 v[100:101], v[2:3], v[196:197], v[100:101]
	v_pk_fma_f32 v[102:103], v[4:5], v[198:199], v[102:103]
	global_store_dwordx4 v79, v[100:103], s[10:11] offset:0 nt
	v_pk_mul_f32 v[200:201], v[200:201], v[156:157] op_sel_hi:[1,0]
	v_pk_mul_f32 v[202:203], v[202:203], v[156:157] op_sel_hi:[1,0]
	v_pk_fma_f32 v[104:105], v[6:7], v[200:201], v[104:105]
	v_pk_fma_f32 v[106:107], v[8:9], v[202:203], v[106:107]
	global_store_dwordx4 v79, v[104:107], s[10:11] offset:1024 nt
	v_pk_mul_f32 v[204:205], v[204:205], v[156:157] op_sel_hi:[1,0]
	v_pk_mul_f32 v[206:207], v[206:207], v[156:157] op_sel_hi:[1,0]
	v_pk_fma_f32 v[108:109], v[10:11], v[204:205], v[108:109]
	v_pk_fma_f32 v[110:111], v[12:13], v[206:207], v[110:111]
	global_store_dwordx4 v79, v[108:111], s[10:11] offset:2048 nt
	v_pk_mul_f32 v[208:209], v[208:209], v[156:157] op_sel_hi:[1,0]
	v_pk_mul_f32 v[210:211], v[210:211], v[156:157] op_sel_hi:[1,0]
	v_pk_fma_f32 v[112:113], v[14:15], v[208:209], v[112:113]
	v_pk_fma_f32 v[114:115], v[16:17], v[210:211], v[114:115]
	global_store_dwordx4 v79, v[112:115], s[10:11] offset:3072 nt
	s_add_u32 s2, s21, 2
	s_lshl_b32 s2, s2, 12
	s_add_u32 s10, s72, s2
	s_addc_u32 s11, s73, 0
	v_pk_mul_f32 v[212:213], v[212:213], v[164:165] op_sel_hi:[1,0]
	v_pk_mul_f32 v[214:215], v[214:215], v[164:165] op_sel_hi:[1,0]
	v_pk_fma_f32 v[116:117], v[2:3], v[212:213], v[116:117]
	v_pk_fma_f32 v[118:119], v[4:5], v[214:215], v[118:119]
	global_store_dwordx4 v79, v[116:119], s[10:11] offset:0 nt
	v_pk_mul_f32 v[216:217], v[216:217], v[164:165] op_sel_hi:[1,0]
	v_pk_mul_f32 v[218:219], v[218:219], v[164:165] op_sel_hi:[1,0]
	v_pk_fma_f32 v[120:121], v[6:7], v[216:217], v[120:121]
	v_pk_fma_f32 v[122:123], v[8:9], v[218:219], v[122:123]
	global_store_dwordx4 v79, v[120:123], s[10:11] offset:1024 nt
	v_pk_mul_f32 v[220:221], v[220:221], v[164:165] op_sel_hi:[1,0]
	v_pk_mul_f32 v[222:223], v[222:223], v[164:165] op_sel_hi:[1,0]
	v_pk_fma_f32 v[124:125], v[10:11], v[220:221], v[124:125]
	v_pk_fma_f32 v[126:127], v[12:13], v[222:223], v[126:127]
	global_store_dwordx4 v79, v[124:127], s[10:11] offset:2048 nt
	v_pk_mul_f32 v[224:225], v[224:225], v[164:165] op_sel_hi:[1,0]
	v_pk_mul_f32 v[226:227], v[226:227], v[164:165] op_sel_hi:[1,0]
	v_pk_fma_f32 v[128:129], v[14:15], v[224:225], v[128:129]
	v_pk_fma_f32 v[130:131], v[16:17], v[226:227], v[130:131]
	global_store_dwordx4 v79, v[128:131], s[10:11] offset:3072 nt
	s_add_u32 s2, s21, 3
	s_lshl_b32 s2, s2, 12
	s_add_u32 s10, s72, s2
	s_addc_u32 s11, s73, 0
	v_pk_mul_f32 v[228:229], v[228:229], v[172:173] op_sel_hi:[1,0]
	v_pk_mul_f32 v[230:231], v[230:231], v[172:173] op_sel_hi:[1,0]
	v_pk_fma_f32 v[132:133], v[2:3], v[228:229], v[132:133]
	v_pk_fma_f32 v[134:135], v[4:5], v[230:231], v[134:135]
	global_store_dwordx4 v79, v[132:135], s[10:11] offset:0 nt
	v_pk_mul_f32 v[232:233], v[232:233], v[172:173] op_sel_hi:[1,0]
	v_pk_mul_f32 v[234:235], v[234:235], v[172:173] op_sel_hi:[1,0]
	v_pk_fma_f32 v[136:137], v[6:7], v[232:233], v[136:137]
	v_pk_fma_f32 v[138:139], v[8:9], v[234:235], v[138:139]
	global_store_dwordx4 v79, v[136:139], s[10:11] offset:1024 nt
	v_pk_mul_f32 v[236:237], v[236:237], v[172:173] op_sel_hi:[1,0]
	v_pk_mul_f32 v[238:239], v[238:239], v[172:173] op_sel_hi:[1,0]
	v_pk_fma_f32 v[140:141], v[10:11], v[236:237], v[140:141]
	v_pk_fma_f32 v[142:143], v[12:13], v[238:239], v[142:143]
	global_store_dwordx4 v79, v[140:143], s[10:11] offset:2048 nt
	v_pk_mul_f32 v[240:241], v[240:241], v[172:173] op_sel_hi:[1,0]
	v_pk_mul_f32 v[242:243], v[242:243], v[172:173] op_sel_hi:[1,0]
	v_pk_fma_f32 v[144:145], v[14:15], v[240:241], v[144:145]
	v_pk_fma_f32 v[146:147], v[16:17], v[242:243], v[146:147]
	global_store_dwordx4 v79, v[144:147], s[10:11] offset:3072 nt
	s_nop 1
	s_add_u32 s2, s21, 4
	s_mul_i32 s12, s2, 0x3000
	s_add_u32 s10, s74, 0x39c4000
	s_addc_u32 s11, s75, 0
	s_add_u32 s10, s10, s12
	s_addc_u32 s11, s11, 0
	global_load_dwordx2 v[148:149], v80, s[10:11] offset:0 nt
	global_load_dwordx2 v[150:151], v80, s[10:11] offset:512 nt
	global_load_dwordx2 v[152:153], v80, s[10:11] offset:1024 nt
	global_load_dwordx2 v[154:155], v80, s[10:11] offset:1536 nt
	s_cmpk_lt_u32 s2, 0x2000
	s_cselect_b32 s10, s4, s6
	s_cselect_b32 s11, s5, s7
	s_and_b32 s12, s2, 0x1fff
	s_lshl_b32 s12, s12, 12
	s_add_u32 s10, s10, s12
	s_addc_u32 s11, s11, 0
	global_load_dwordx4 v[84:87], v79, s[10:11] offset:0 nt
	global_load_dwordx4 v[88:91], v79, s[10:11] offset:1024 nt
	global_load_dwordx4 v[92:95], v79, s[10:11] offset:2048 nt
	global_load_dwordx4 v[96:99], v79, s[10:11] offset:3072 nt
	s_cmp_eq_u32 s28, 0
	s_cbranch_scc1 .Lp7n_nocol_4
	s_and_b32 s12, s2, 63
	s_lshl_b32 s12, s12, 10
	s_add_u32 s10, s74, 0x94000
	s_addc_u32 s11, s75, 0
	s_add_u32 s10, s10, s12
	s_addc_u32 s11, s11, 0
	global_load_dwordx4 v[18:21], v79, s[10:11]
	s_add_u32 s10, s10, 0x10000
	s_addc_u32 s11, s11, 0
	global_load_dwordx4 v[22:25], v79, s[10:11]
.Lp7n_nocol_4:
	s_add_u32 s2, s21, 5
	s_mul_i32 s12, s2, 0x3000
	s_add_u32 s10, s74, 0x39c4000
	s_addc_u32 s11, s75, 0
	s_add_u32 s10, s10, s12
	s_addc_u32 s11, s11, 0
	global_load_dwordx2 v[156:157], v80, s[10:11] offset:0 nt
	global_load_dwordx2 v[158:159], v80, s[10:11] offset:512 nt
	global_load_dwordx2 v[160:161], v80, s[10:11] offset:1024 nt
	global_load_dwordx2 v[162:163], v80, s[10:11] offset:1536 nt
	s_cmpk_lt_u32 s2, 0x2000
	s_cselect_b32 s10, s4, s6
	s_cselect_b32 s11, s5, s7
	s_and_b32 s12, s2, 0x1fff
	s_lshl_b32 s12, s12, 12
	s_add_u32 s10, s10, s12
	s_addc_u32 s11, s11, 0
	global_load_dwordx4 v[100:103], v79, s[10:11] offset:0 nt
	global_load_dwordx4 v[104:107], v79, s[10:11] offset:1024 nt
	global_load_dwordx4 v[108:111], v79, s[10:11] offset:2048 nt
	global_load_dwordx4 v[112:115], v79, s[10:11] offset:3072 nt
	s_cmp_eq_u32 s28, 0
	s_cbranch_scc1 .Lp7n_nocol_5
	s_and_b32 s12, s2, 63
	s_lshl_b32 s12, s12, 10
	s_add_u32 s10, s74, 0x94000
	s_addc_u32 s11, s75, 0
	s_add_u32 s10, s10, s12
	s_addc_u32 s11, s11, 0
	global_load_dwordx4 v[26:29], v79, s[10:11]
	s_add_u32 s10, s10, 0x10000
	s_addc_u32 s11, s11, 0
	global_load_dwordx4 v[30:33], v79, s[10:11]
.Lp7n_nocol_5:
	s_add_u32 s2, s21, 6
	s_mul_i32 s12, s2, 0x3000
	s_add_u32 s10, s74, 0x39c4000
	s_addc_u32 s11, s75, 0
	s_add_u32 s10, s10, s12
	s_addc_u32 s11, s11, 0
	global_load_dwordx2 v[164:165], v80, s[10:11] offset:0 nt
	global_load_dwordx2 v[166:167], v80, s[10:11] offset:512 nt
	global_load_dwordx2 v[168:169], v80, s[10:11] offset:1024 nt
	global_load_dwordx2 v[170:171], v80, s[10:11] offset:1536 nt
	s_cmpk_lt_u32 s2, 0x2000
	s_cselect_b32 s10, s4, s6
	s_cselect_b32 s11, s5, s7
	s_and_b32 s12, s2, 0x1fff
	s_lshl_b32 s12, s12, 12
	s_add_u32 s10, s10, s12
	s_addc_u32 s11, s11, 0
	global_load_dwordx4 v[116:119], v79, s[10:11] offset:0 nt
	global_load_dwordx4 v[120:123], v79, s[10:11] offset:1024 nt
	global_load_dwordx4 v[124:127], v79, s[10:11] offset:2048 nt
	global_load_dwordx4 v[128:131], v79, s[10:11] offset:3072 nt
	s_cmp_eq_u32 s28, 0
	s_cbranch_scc1 .Lp7n_nocol_6
	s_and_b32 s12, s2, 63
	s_lshl_b32 s12, s12, 10
	s_add_u32 s10, s74, 0x94000
	s_addc_u32 s11, s75, 0
	s_add_u32 s10, s10, s12
	s_addc_u32 s11, s11, 0
	global_load_dwordx4 v[46:49], v79, s[10:11]
	s_add_u32 s10, s10, 0x10000
	s_addc_u32 s11, s11, 0
	global_load_dwordx4 v[50:53], v79, s[10:11]
.Lp7n_nocol_6:
	s_add_u32 s2, s21, 7
	s_mul_i32 s12, s2, 0x3000
	s_add_u32 s10, s74, 0x39c4000
	s_addc_u32 s11, s75, 0
	s_add_u32 s10, s10, s12
	s_addc_u32 s11, s11, 0
	global_load_dwordx2 v[172:173], v80, s[10:11] offset:0 nt
	global_load_dwordx2 v[174:175], v80, s[10:11] offset:512 nt
	global_load_dwordx2 v[176:177], v80, s[10:11] offset:1024 nt
	global_load_dwordx2 v[178:179], v80, s[10:11] offset:1536 nt
	s_cmpk_lt_u32 s2, 0x2000
	s_cselect_b32 s10, s4, s6
	s_cselect_b32 s11, s5, s7
	s_and_b32 s12, s2, 0x1fff
	s_lshl_b32 s12, s12, 12
	s_add_u32 s10, s10, s12
	s_addc_u32 s11, s11, 0
	global_load_dwordx4 v[132:135], v79, s[10:11] offset:0 nt
	global_load_dwordx4 v[136:139], v79, s[10:11] offset:1024 nt
	global_load_dwordx4 v[140:143], v79, s[10:11] offset:2048 nt
	global_load_dwordx4 v[144:147], v79, s[10:11] offset:3072 nt
	s_cmp_eq_u32 s28, 0
	s_cbranch_scc1 .Lp7n_nocol_7
	s_and_b32 s12, s2, 63
	s_lshl_b32 s12, s12, 10
	s_add_u32 s10, s74, 0x94000
	s_addc_u32 s11, s75, 0
	s_add_u32 s10, s10, s12
	s_addc_u32 s11, s11, 0
	global_load_dwordx4 v[54:57], v79, s[10:11]
	s_add_u32 s10, s10, 0x10000
	s_addc_u32 s11, s11, 0
	global_load_dwordx4 v[58:61], v79, s[10:11]

.Lp7n_nope_1:
	v_lshlrev_b32_e32 v180, 16, v148
	v_and_b32_e32 v181, 0xffff0000, v148
	v_lshlrev_b32_e32 v182, 16, v149
	v_and_b32_e32 v183, 0xffff0000, v149
	v_lshlrev_b32_e32 v184, 16, v150
	v_and_b32_e32 v185, 0xffff0000, v150
	v_lshlrev_b32_e32 v186, 16, v151
	v_and_b32_e32 v187, 0xffff0000, v151
	v_lshlrev_b32_e32 v188, 16, v152
	v_and_b32_e32 v189, 0xffff0000, v152
	v_lshlrev_b32_e32 v190, 16, v153
	v_and_b32_e32 v191, 0xffff0000, v153
	v_lshlrev_b32_e32 v192, 16, v154
	v_and_b32_e32 v193, 0xffff0000, v154
	v_lshlrev_b32_e32 v194, 16, v155
	v_and_b32_e32 v195, 0xffff0000, v155
	v_lshlrev_b32_e32 v196, 16, v156
	v_and_b32_e32 v197, 0xffff0000, v156
	v_lshlrev_b32_e32 v198, 16, v157
	v_and_b32_e32 v199, 0xffff0000, v157
	v_lshlrev_b32_e32 v200, 16, v158
	v_and_b32_e32 v201, 0xffff0000, v158
	v_lshlrev_b32_e32 v202, 16, v159
	v_and_b32_e32 v203, 0xffff0000, v159
	v_lshlrev_b32_e32 v204, 16, v160
	v_and_b32_e32 v205, 0xffff0000, v160
	v_lshlrev_b32_e32 v206, 16, v161
	v_and_b32_e32 v207, 0xffff0000, v161
	v_lshlrev_b32_e32 v208, 16, v162
	v_and_b32_e32 v209, 0xffff0000, v162
	v_lshlrev_b32_e32 v210, 16, v163
	v_and_b32_e32 v211, 0xffff0000, v163
	v_lshlrev_b32_e32 v212, 16, v164
	v_and_b32_e32 v213, 0xffff0000, v164
	v_lshlrev_b32_e32 v214, 16, v165
	v_and_b32_e32 v215, 0xffff0000, v165
	v_lshlrev_b32_e32 v216, 16, v166
	v_and_b32_e32 v217, 0xffff0000, v166
	v_lshlrev_b32_e32 v218, 16, v167
	v_and_b32_e32 v219, 0xffff0000, v167
	v_lshlrev_b32_e32 v220, 16, v168
	v_and_b32_e32 v221, 0xffff0000, v168
	v_lshlrev_b32_e32 v222, 16, v169
	v_and_b32_e32 v223, 0xffff0000, v169
	v_lshlrev_b32_e32 v224, 16, v170
	v_and_b32_e32 v225, 0xffff0000, v170
	v_lshlrev_b32_e32 v226, 16, v171
	v_and_b32_e32 v227, 0xffff0000, v171
	v_lshlrev_b32_e32 v228, 16, v172
	v_and_b32_e32 v229, 0xffff0000, v172
	v_lshlrev_b32_e32 v230, 16, v173
	v_and_b32_e32 v231, 0xffff0000, v173
	v_lshlrev_b32_e32 v232, 16, v174
	v_and_b32_e32 v233, 0xffff0000, v174
	v_lshlrev_b32_e32 v234, 16, v175
	v_and_b32_e32 v235, 0xffff0000, v175
	v_lshlrev_b32_e32 v236, 16, v176
	v_and_b32_e32 v237, 0xffff0000, v176
	v_lshlrev_b32_e32 v238, 16, v177
	v_and_b32_e32 v239, 0xffff0000, v177
	v_lshlrev_b32_e32 v240, 16, v178
	v_and_b32_e32 v241, 0xffff0000, v178
	v_lshlrev_b32_e32 v242, 16, v179
	v_and_b32_e32 v243, 0xffff0000, v179
	v_pk_mul_f32 v[148:149], v[180:181], v[180:181]
	v_pk_mul_f32 v[156:157], v[196:197], v[196:197]
	v_pk_mul_f32 v[164:165], v[212:213], v[212:213]
	v_pk_mul_f32 v[172:173], v[228:229], v[228:229]
	v_pk_fma_f32 v[148:149], v[182:183], v[182:183], v[148:149]
	v_pk_fma_f32 v[156:157], v[198:199], v[198:199], v[156:157]
	v_pk_fma_f32 v[164:165], v[214:215], v[214:215], v[164:165]
	v_pk_fma_f32 v[172:173], v[230:231], v[230:231], v[172:173]
	v_pk_fma_f32 v[148:149], v[184:185], v[184:185], v[148:149]
	v_pk_fma_f32 v[156:157], v[200:201], v[200:201], v[156:157]
	v_pk_fma_f32 v[164:165], v[216:217], v[216:217], v[164:165]
	v_pk_fma_f32 v[172:173], v[232:233], v[232:233], v[172:173]
	v_pk_fma_f32 v[148:149], v[186:187], v[186:187], v[148:149]
	v_pk_fma_f32 v[156:157], v[202:203], v[202:203], v[156:157]
	v_pk_fma_f32 v[164:165], v[218:219], v[218:219], v[164:165]
	v_pk_fma_f32 v[172:173], v[234:235], v[234:235], v[172:173]
	v_pk_fma_f32 v[148:149], v[188:189], v[188:189], v[148:149]
	v_pk_fma_f32 v[156:157], v[204:205], v[204:205], v[156:157]
	v_pk_fma_f32 v[164:165], v[220:221], v[220:221], v[164:165]
	v_pk_fma_f32 v[172:173], v[236:237], v[236:237], v[172:173]
	v_pk_fma_f32 v[148:149], v[190:191], v[190:191], v[148:149]
	v_pk_fma_f32 v[156:157], v[206:207], v[206:207], v[156:157]
	v_pk_fma_f32 v[164:165], v[222:223], v[222:223], v[164:165]
	v_pk_fma_f32 v[172:173], v[238:239], v[238:239], v[172:173]
	v_pk_fma_f32 v[148:149], v[192:193], v[192:193], v[148:149]
	v_pk_fma_f32 v[156:157], v[208:209], v[208:209], v[156:157]
	v_pk_fma_f32 v[164:165], v[224:225], v[224:225], v[164:165]
	v_pk_fma_f32 v[172:173], v[240:241], v[240:241], v[172:173]
	v_pk_fma_f32 v[148:149], v[194:195], v[194:195], v[148:149]
	v_pk_fma_f32 v[156:157], v[210:211], v[210:211], v[156:157]
	v_pk_fma_f32 v[164:165], v[226:227], v[226:227], v[164:165]
	v_pk_fma_f32 v[172:173], v[242:243], v[242:243], v[172:173]
	v_add_f32_e32 v148, v148, v149
	v_add_f32_e32 v156, v156, v157
	v_add_f32_e32 v164, v164, v165
	v_add_f32_e32 v172, v172, v173
	ds_bpermute_b32 v149, v35, v148
	ds_bpermute_b32 v157, v35, v156
	ds_bpermute_b32 v165, v35, v164
	ds_bpermute_b32 v173, v35, v172
	s_waitcnt lgkmcnt(0)
	v_add_f32_e32 v148, v148, v149
	v_add_f32_e32 v156, v156, v157
	v_add_f32_e32 v164, v164, v165
	v_add_f32_e32 v172, v172, v173
	ds_bpermute_b32 v149, v70, v148
	ds_bpermute_b32 v157, v70, v156
	ds_bpermute_b32 v165, v70, v164
	ds_bpermute_b32 v173, v70, v172
	s_waitcnt lgkmcnt(0)
	v_add_f32_e32 v148, v148, v149
	v_add_f32_e32 v156, v156, v157
	v_add_f32_e32 v164, v164, v165
	v_add_f32_e32 v172, v172, v173
	ds_bpermute_b32 v149, v71, v148
	ds_bpermute_b32 v157, v71, v156
	ds_bpermute_b32 v165, v71, v164
	ds_bpermute_b32 v173, v71, v172
	s_waitcnt lgkmcnt(0)
	v_add_f32_e32 v148, v148, v149
	v_add_f32_e32 v156, v156, v157
	v_add_f32_e32 v164, v164, v165
	v_add_f32_e32 v172, v172, v173
	ds_bpermute_b32 v149, v72, v148
	ds_bpermute_b32 v157, v72, v156
	ds_bpermute_b32 v165, v72, v164
	ds_bpermute_b32 v173, v72, v172
	s_waitcnt lgkmcnt(0)
	v_add_f32_e32 v148, v148, v149
	v_add_f32_e32 v156, v156, v157
	v_add_f32_e32 v164, v164, v165
	v_add_f32_e32 v172, v172, v173
	ds_bpermute_b32 v149, v73, v148
	ds_bpermute_b32 v157, v73, v156
	ds_bpermute_b32 v165, v73, v164
	ds_bpermute_b32 v173, v73, v172
	s_waitcnt lgkmcnt(0)
	v_add_f32_e32 v148, v148, v149
	v_add_f32_e32 v156, v156, v157
	v_add_f32_e32 v164, v164, v165
	v_add_f32_e32 v172, v172, v173
	ds_bpermute_b32 v149, v74, v148
	ds_bpermute_b32 v157, v74, v156
	ds_bpermute_b32 v165, v74, v164
	ds_bpermute_b32 v173, v74, v172
	s_waitcnt lgkmcnt(0)
	v_add_f32_e32 v148, v148, v149
	v_add_f32_e32 v156, v156, v157
	v_add_f32_e32 v164, v164, v165
	v_add_f32_e32 v172, v172, v173
	v_fmamk_f32 v148, v148, 0x3a800000, v77
	v_fmamk_f32 v156, v156, 0x3a800000, v77
	v_fmamk_f32 v164, v164, 0x3a800000, v77
	v_fmamk_f32 v172, v172, 0x3a800000, v77
	v_mul_f32_e32 v150, 0x4b800000, v148
	v_cmp_gt_f32_e32 vcc, s26, v148
	s_nop 1
	v_cndmask_b32_e32 v148, v148, v150, vcc
	v_rsq_f32_e32 v148, v148
	s_nop 0
	v_mul_f32_e32 v150, 0x45800000, v148
	v_cndmask_b32_e32 v148, v148, v150, vcc
	v_mul_f32_e32 v158, 0x4b800000, v156
	v_cmp_gt_f32_e32 vcc, s26, v156
	s_nop 1
	v_cndmask_b32_e32 v156, v156, v158, vcc
	v_rsq_f32_e32 v156, v156
	s_nop 0
	v_mul_f32_e32 v158, 0x45800000, v156
	v_cndmask_b32_e32 v156, v156, v158, vcc
	v_mul_f32_e32 v166, 0x4b800000, v164
	v_cmp_gt_f32_e32 vcc, s26, v164
	s_nop 1
	v_cndmask_b32_e32 v164, v164, v166, vcc
	v_rsq_f32_e32 v164, v164
	s_nop 0
	v_mul_f32_e32 v166, 0x45800000, v164
	v_cndmask_b32_e32 v164, v164, v166, vcc
	v_mul_f32_e32 v174, 0x4b800000, v172
	v_cmp_gt_f32_e32 vcc, s26, v172
	s_nop 1
	v_cndmask_b32_e32 v172, v172, v174, vcc
	v_rsq_f32_e32 v172, v172
	s_nop 0
	v_mul_f32_e32 v174, 0x45800000, v172
	v_cndmask_b32_e32 v172, v172, v174, vcc
	s_add_u32 s2, s21, 4
	s_lshl_b32 s2, s2, 12
	s_add_u32 s10, s72, s2
	s_addc_u32 s11, s73, 0
	v_pk_mul_f32 v[180:181], v[180:181], v[148:149] op_sel_hi:[1,0]
	v_pk_mul_f32 v[182:183], v[182:183], v[148:149] op_sel_hi:[1,0]
	v_pk_fma_f32 v[84:85], v[2:3], v[180:181], v[84:85]
	v_pk_fma_f32 v[86:87], v[4:5], v[182:183], v[86:87]
	global_store_dwordx4 v79, v[84:87], s[10:11] offset:0 nt
	v_pk_mul_f32 v[184:185], v[184:185], v[148:149] op_sel_hi:[1,0]
	v_pk_mul_f32 v[186:187], v[186:187], v[148:149] op_sel_hi:[1,0]
	v_pk_fma_f32 v[88:89], v[6:7], v[184:185], v[88:89]
	v_pk_fma_f32 v[90:91], v[8:9], v[186:187], v[90:91]
	global_store_dwordx4 v79, v[88:91], s[10:11] offset:1024 nt
	v_pk_mul_f32 v[188:189], v[188:189], v[148:149] op_sel_hi:[1,0]
	v_pk_mul_f32 v[190:191], v[190:191], v[148:149] op_sel_hi:[1,0]
	v_pk_fma_f32 v[92:93], v[10:11], v[188:189], v[92:93]
	v_pk_fma_f32 v[94:95], v[12:13], v[190:191], v[94:95]
	global_store_dwordx4 v79, v[92:95], s[10:11] offset:2048 nt
	v_pk_mul_f32 v[192:193], v[192:193], v[148:149] op_sel_hi:[1,0]
	v_pk_mul_f32 v[194:195], v[194:195], v[148:149] op_sel_hi:[1,0]
	v_pk_fma_f32 v[96:97], v[14:15], v[192:193], v[96:97]
	v_pk_fma_f32 v[98:99], v[16:17], v[194:195], v[98:99]
	global_store_dwordx4 v79, v[96:99], s[10:11] offset:3072 nt
	s_add_u32 s2, s21, 5
	s_lshl_b32 s2, s2, 12
	s_add_u32 s10, s72, s2
	s_addc_u32 s11, s73, 0
	v_pk_mul_f32 v[196:197], v[196:197], v[156:157] op_sel_hi:[1,0]
	v_pk_mul_f32 v[198:199], v[198:199], v[156:157] op_sel_hi:[1,0]
	v_pk_fma_f32 v[100:101], v[2:3], v[196:197], v[100:101]
	v_pk_fma_f32 v[102:103], v[4:5], v[198:199], v[102:103]
	global_store_dwordx4 v79, v[100:103], s[10:11] offset:0 nt
	v_pk_mul_f32 v[200:201], v[200:201], v[156:157] op_sel_hi:[1,0]
	v_pk_mul_f32 v[202:203], v[202:203], v[156:157] op_sel_hi:[1,0]
	v_pk_fma_f32 v[104:105], v[6:7], v[200:201], v[104:105]
	v_pk_fma_f32 v[106:107], v[8:9], v[202:203], v[106:107]
	global_store_dwordx4 v79, v[104:107], s[10:11] offset:1024 nt
	v_pk_mul_f32 v[204:205], v[204:205], v[156:157] op_sel_hi:[1,0]
	v_pk_mul_f32 v[206:207], v[206:207], v[156:157] op_sel_hi:[1,0]
	v_pk_fma_f32 v[108:109], v[10:11], v[204:205], v[108:109]
	v_pk_fma_f32 v[110:111], v[12:13], v[206:207], v[110:111]
	global_store_dwordx4 v79, v[108:111], s[10:11] offset:2048 nt
	v_pk_mul_f32 v[208:209], v[208:209], v[156:157] op_sel_hi:[1,0]
	v_pk_mul_f32 v[210:211], v[210:211], v[156:157] op_sel_hi:[1,0]
	v_pk_fma_f32 v[112:113], v[14:15], v[208:209], v[112:113]
	v_pk_fma_f32 v[114:115], v[16:17], v[210:211], v[114:115]
	global_store_dwordx4 v79, v[112:115], s[10:11] offset:3072 nt
	s_add_u32 s2, s21, 6
	s_lshl_b32 s2, s2, 12
	s_add_u32 s10, s72, s2
	s_addc_u32 s11, s73, 0
	v_pk_mul_f32 v[212:213], v[212:213], v[164:165] op_sel_hi:[1,0]
	v_pk_mul_f32 v[214:215], v[214:215], v[164:165] op_sel_hi:[1,0]
	v_pk_fma_f32 v[116:117], v[2:3], v[212:213], v[116:117]
	v_pk_fma_f32 v[118:119], v[4:5], v[214:215], v[118:119]
	global_store_dwordx4 v79, v[116:119], s[10:11] offset:0 nt
	v_pk_mul_f32 v[216:217], v[216:217], v[164:165] op_sel_hi:[1,0]
	v_pk_mul_f32 v[218:219], v[218:219], v[164:165] op_sel_hi:[1,0]
	v_pk_fma_f32 v[120:121], v[6:7], v[216:217], v[120:121]
	v_pk_fma_f32 v[122:123], v[8:9], v[218:219], v[122:123]
	global_store_dwordx4 v79, v[120:123], s[10:11] offset:1024 nt
	v_pk_mul_f32 v[220:221], v[220:221], v[164:165] op_sel_hi:[1,0]
	v_pk_mul_f32 v[222:223], v[222:223], v[164:165] op_sel_hi:[1,0]
	v_pk_fma_f32 v[124:125], v[10:11], v[220:221], v[124:125]
	v_pk_fma_f32 v[126:127], v[12:13], v[222:223], v[126:127]
	global_store_dwordx4 v79, v[124:127], s[10:11] offset:2048 nt
	v_pk_mul_f32 v[224:225], v[224:225], v[164:165] op_sel_hi:[1,0]
	v_pk_mul_f32 v[226:227], v[226:227], v[164:165] op_sel_hi:[1,0]
	v_pk_fma_f32 v[128:129], v[14:15], v[224:225], v[128:129]
	v_pk_fma_f32 v[130:131], v[16:17], v[226:227], v[130:131]
	global_store_dwordx4 v79, v[128:131], s[10:11] offset:3072 nt
	s_add_u32 s2, s21, 7
	s_lshl_b32 s2, s2, 12
	s_add_u32 s10, s72, s2
	s_addc_u32 s11, s73, 0
	v_pk_mul_f32 v[228:229], v[228:229], v[172:173] op_sel_hi:[1,0]
	v_pk_mul_f32 v[230:231], v[230:231], v[172:173] op_sel_hi:[1,0]
	v_pk_fma_f32 v[132:133], v[2:3], v[228:229], v[132:133]
	v_pk_fma_f32 v[134:135], v[4:5], v[230:231], v[134:135]
	global_store_dwordx4 v79, v[132:135], s[10:11] offset:0 nt
	v_pk_mul_f32 v[232:233], v[232:233], v[172:173] op_sel_hi:[1,0]
	v_pk_mul_f32 v[234:235], v[234:235], v[172:173] op_sel_hi:[1,0]
	v_pk_fma_f32 v[136:137], v[6:7], v[232:233], v[136:137]
	v_pk_fma_f32 v[138:139], v[8:9], v[234:235], v[138:139]
	global_store_dwordx4 v79, v[136:139], s[10:11] offset:1024 nt
	v_pk_mul_f32 v[236:237], v[236:237], v[172:173] op_sel_hi:[1,0]
	v_pk_mul_f32 v[238:239], v[238:239], v[172:173] op_sel_hi:[1,0]
	v_pk_fma_f32 v[140:141], v[10:11], v[236:237], v[140:141]
	v_pk_fma_f32 v[142:143], v[12:13], v[238:239], v[142:143]
	global_store_dwordx4 v79, v[140:143], s[10:11] offset:2048 nt
	v_pk_mul_f32 v[240:241], v[240:241], v[172:173] op_sel_hi:[1,0]
	v_pk_mul_f32 v[242:243], v[242:243], v[172:173] op_sel_hi:[1,0]
	v_pk_fma_f32 v[144:145], v[14:15], v[240:241], v[144:145]
	v_pk_fma_f32 v[146:147], v[16:17], v[242:243], v[146:147]
	global_store_dwordx4 v79, v[144:147], s[10:11] offset:3072 nt
	s_nop 1
	s_branch .LBB0_1002

	.amdhsa_kernel _Z14fwd_megakernel6Params
		.amdhsa_group_segment_fixed_size 0
		.amdhsa_private_segment_fixed_size 0
		.amdhsa_kernarg_size 464
		.amdhsa_user_sgpr_count 2
		.amdhsa_user_sgpr_dispatch_ptr 0
		.amdhsa_user_sgpr_queue_ptr 0
		.amdhsa_user_sgpr_kernarg_segment_ptr 1
		.amdhsa_user_sgpr_dispatch_id 0
		.amdhsa_user_sgpr_kernarg_preload_length 0
		.amdhsa_user_sgpr_kernarg_preload_offset 0
		.amdhsa_user_sgpr_private_segment_size 0
		.amdhsa_uses_dynamic_stack 0
		.amdhsa_enable_private_segment 0
		.amdhsa_system_sgpr_workgroup_id_x 1
		.amdhsa_system_sgpr_workgroup_id_y 0
		.amdhsa_system_sgpr_workgroup_id_z 0
		.amdhsa_system_sgpr_workgroup_info 0
		.amdhsa_system_vgpr_workitem_id 0
		.amdhsa_next_free_vgpr 256
		.amdhsa_next_free_sgpr 102
		.amdhsa_accum_offset 256
		.amdhsa_reserve_vcc 1
		.amdhsa_float_round_mode_32 0
		.amdhsa_float_round_mode_16_64 0
		.amdhsa_float_denorm_mode_32 3
		.amdhsa_float_denorm_mode_16_64 3
		.amdhsa_dx10_clamp 1
		.amdhsa_ieee_mode 1
		.amdhsa_fp16_overflow 0
		.amdhsa_tg_split 0
		.amdhsa_exception_fp_ieee_invalid_op 0
		.amdhsa_exception_fp_denorm_src 0
		.amdhsa_exception_fp_ieee_div_zero 0
		.amdhsa_exception_fp_ieee_overflow 0
		.amdhsa_exception_fp_ieee_underflow 0
		.amdhsa_exception_fp_ieee_inexact 0
		.amdhsa_exception_int_div_zero 0
	.end_amdhsa_kernel

amdhsa.kernels:
  - .agpr_count:     0
    .args:
      - .offset:         0
        .size:           208
        .value_kind:     by_value
      - .offset:         208
        .size:           4
        .value_kind:     hidden_block_count_x
      - .offset:         212
        .size:           4
        .value_kind:     hidden_block_count_y
      - .offset:         216
        .size:           4
        .value_kind:     hidden_block_count_z
      - .offset:         220
        .size:           2
        .value_kind:     hidden_group_size_x
      - .offset:         222
        .size:           2
        .value_kind:     hidden_group_size_y
      - .offset:         224
        .size:           2
        .value_kind:     hidden_group_size_z
      - .offset:         226
        .size:           2
        .value_kind:     hidden_remainder_x
      - .offset:         228
        .size:           2
        .value_kind:     hidden_remainder_y
      - .offset:         230
        .size:           2
        .value_kind:     hidden_remainder_z
      - .offset:         248
        .size:           8
        .value_kind:     hidden_global_offset_x
      - .offset:         256
        .size:           8
        .value_kind:     hidden_global_offset_y
      - .offset:         264
        .size:           8
        .value_kind:     hidden_global_offset_z
      - .offset:         272
        .size:           2
        .value_kind:     hidden_grid_dims
      - .offset:         328
        .size:           4
        .value_kind:     hidden_dynamic_lds_size
    .group_segment_fixed_size: 0
    .kernarg_segment_align: 8
    .kernarg_segment_size: 464
    .language:       OpenCL C
    .language_version:
      - 2
      - 0
    .max_flat_workgroup_size: 512
    .name:           _Z14fwd_megakernel6Params
    .private_segment_fixed_size: 0
    .sgpr_count:     108
    .sgpr_spill_count: 59
    .symbol:         _Z14fwd_megakernel6Params.kd
    .uniform_work_group_size: 1
    .uses_dynamic_stack: false
    .vgpr_count:     256
    .vgpr_spill_count: 0
    .wavefront_size: 64
